# previous + first K-step fragment ds_reads of the next tile hoisted above the per-tile header math (Up, Down, mixer-out)
# baseline (speedup 1.0000x reference)
; #define PG8_STAGE(bufoff, gbase, voff) do { _Pragma("unroll") for (int _i = 0; _i < 2; ++_i) \
;         __builtin_amdgcn_global_load_lds((const unsigned*)((const char*)(gbase) + (voff)[_i]), (PG8_LAS unsigned*)(lds + (bufoff) + ldsw + _i * (8 * USTR)), 16, 0, 0); } while (0)
; #define PG8_LDA(dst, b, h) do { _Pragma("unroll") for (int m = 0; m < 4; ++m) _Pragma("unroll") for (int k = 0; k < 2; ++k) dst[m][k] = *(const PG8_LAS bf16x8*)(lds + PG8_SA(b, h) + aoff + m * (2 * USTR) + k * 64); } while (0)
; #define PG8_LDB(dst, b, h) do { _Pragma("unroll") for (int n = 0; n < 2; ++n) _Pragma("unroll") for (int k = 0; k < 2; ++k) dst[n][k] = *(const PG8_LAS bf16x8*)(lds + PG8_SB(b, h) + boff + n * (2 * USTR) + k * 64); } while (0)
; #define PG8_SCHED __builtin_amdgcn_sched_barrier(0)
;     __host__ __device__ bool next(int i, Unit& u) const {
;         const long L = (long)i * G + c; if (L >= nwg) return false;
;         int wgid = (int)L; { const int q = nwg / NXCD, r = nwg % NXCD, xcd = wgid % NXCD, off = wgid / NXCD; wgid = (xcd < r ? xcd * (q + 1) : r * (q + 1) + (xcd - r) * q) + off; }
;         const int nig = WGM * nN, gid = wgid / nig, fm = gid * WGM, gsz = (nM - fm) < WGM ? (nM - fm) : WGM;
;         u.pm = fm + ((wgid % nig) % gsz); u.pn = (wgid % nig) / gsz; return true;
; template <class Epi, class Sched, bool ALIGN_EPI, bool SP2>
; __device__ __forceinline__ void gemm_phase(PG8_LAS unsigned char* lds, const Gemm g, const Sched& S, const Epi& E, int wid) {
;     ...
;             PG8_LDB(B0, 0, 0); PG8_LDB(B1, 0, 1); PG8_SCHED; PG8_LDA(At, 0, 0); PG8_STAGE(PG8_SA(1, 1), a1 + hstepA, voffA);
.LBB0_143:
	s_add_i32 s95, 0, 0x11000
	s_add_i32 s44, 0, 0x15400
	v_add_u32_e32 v60, s95, v216
	v_add_u32_e32 v156, s44, v216
	ds_read_b128 v[48:51], v60
	ds_read_b128 v[52:55], v60 offset:64
	ds_read_b128 v[56:59], v60 offset:2176
	ds_read_b128 v[60:63], v60 offset:2240
	ds_read_b128 v[144:147], v156
	ds_read_b128 v[148:151], v156 offset:64
	ds_read_b128 v[152:155], v156 offset:2176
	ds_read_b128 v[156:159], v156 offset:2240
	ds_read_b128 v[172:175], v217
	ds_read_b128 v[176:179], v217 offset:64
	ds_read_b128 v[180:183], v217 offset:2176
	ds_read_b128 v[184:187], v217 offset:2240
	ds_read_b128 v[188:191], v217 offset:4352
	ds_read_b128 v[208:211], v217 offset:4416
	ds_read_b128 v[212:215], v217 offset:6528
	ds_read_b128 v[218:221], v217 offset:6592
	s_add_i32 s77, s77, 1
	s_mul_i32 s23, s77, s13
	s_mul_hi_u32 s26, s77, s3
	s_add_i32 s23, s26, s23
	s_mul_i32 s26, s77, s3
	v_readlane_b32 s27, v251, 0
	s_add_u32 s26, s26, s27
	s_addc_u32 s27, s23, s58
	s_waitcnt lgkmcnt(0)
	v_mov_b64_e32 v[0:1], 0x400
	v_cmp_lt_i64_e64 s[36:37], s[26:27], v[0:1]
	v_mov_b64_e32 v[0:1], 0x3ff
	v_cmp_gt_i64_e32 vcc, s[26:27], v[0:1]
	s_cbranch_vccnz .LBB0_149
	s_ashr_i32 s22, s26, 31
	s_lshr_b32 s22, s22, 29
	s_add_i32 s27, s26, s22
	s_and_b32 s22, s27, -8
	s_sub_i32 s26, s26, s22
	s_cmp_gt_i32 s26, -1
	s_mov_b64 s[22:23], -1
	s_cbranch_scc0 .LBB0_146
	s_lshl_b32 s68, s26, 7
	s_mov_b64 s[22:23], 0

; #define PG8_LAS __attribute__((address_space(3)))
; #define PG8_STAGE(bufoff, gbase, voff) do { _Pragma("unroll") for (int _i = 0; _i < 2; ++_i) \
;         __builtin_amdgcn_global_load_lds((const unsigned*)((const char*)(gbase) + (voff)[_i]), (PG8_LAS unsigned*)(lds + (bufoff) + ldsw + _i * (8 * USTR)), 16, 0, 0); } while (0)
; #define PG8_LDA(dst, b, h) do { _Pragma("unroll") for (int m = 0; m < 4; ++m) _Pragma("unroll") for (int k = 0; k < 2; ++k) dst[m][k] = *(const PG8_LAS bf16x8*)(lds + PG8_SA(b, h) + aoff + m * (2 * USTR) + k * 64); } while (0)
; template <class Epi, class Sched, bool ALIGN_EPI, bool SP2>
; __device__ __forceinline__ void gemm_phase(PG8_LAS unsigned char* lds, const Gemm g, const Sched& S, const Epi& E, int wid) {
;     ...
;         const char* nA = has_next ? (const char*)g.A + (size_t)nxt.pm * tstepA : cA; const char* nB = has_next ? (const char*)g.Bt + (size_t)nxt.pn * tstepB : cB;
;         for (int t = 0; t < nt; t += 2) {
;             const bool last = (t == nt - 2);
;             const char* a1 = cA + (size_t)(t + 1) * kstep;
;             const char* a2 = last ? nA : cA + (size_t)(t + 2) * kstep; const char* b2 = last ? nB : cB + (size_t)(t + 2) * kstep;
;             const char* a3 = a2 + kstep; const char* b3 = b2 + kstep;
;             if constexpr (Epi::PRE == 1) { if (last) {
;                 const char* rsrc; const char* ssrc; E.pre(cur, rsrc, ssrc);
; #pragma unroll
;                 for (int _i = 0; _i < 2; ++_i) __builtin_amdgcn_global_load_lds((const unsigned*)(rsrc + (wid + 8 * _i) * 1024 + lane * 16), (PG8_LAS unsigned*)(lds + LDS_XOFF + (wid + 8 * _i) * 1024), 16, 0, 0);
;                 if (wid == 0) __builtin_amdgcn_global_load_lds((const unsigned*)(ssrc + lane * 16), (PG8_LAS unsigned*)(lds + LDS_XOFF + 16384), 16, 0, 0);
;             } }
;             if constexpr (SP2) {
;             PG8_LDB(B0, 0, 0); PG8_LDB(B1, 0, 1); PG8_SCHED; PG8_LDA(At, 0, 0); PG8_STAGE(PG8_SA(1, 1), a1 + hstepA, voffA);
;             PG8_WAIT_V(8); PG8_WAIT_L(0); PG8_BAR; PG8_MMA(0, 0, At, B0); PG8_MMA(0, 1, At, B1); PG8_BAR; PG8_SCHED;
;             PG8_LDA(At, 0, 1); PG8_STAGE(PG8_SB(0, 0), b2, voffB); PG8_STAGE(PG8_SB(0, 1), b2 + hstepB, voffB); PG8_STAGE(PG8_SA(0, 0), a2, voffA);
;             PG8_WAIT_V(8); PG8_WAIT_L(0); PG8_BAR; PG8_MMA(1, 0, At, B0); PG8_MMA(1, 1, At, B1); PG8_BAR; PG8_SCHED;
.Lhb_mixout:
	s_add_u32 s40, s38, 0xfff80080
	s_addc_u32 s41, s39, -1
	s_add_i32 s95, 0, 0x11000
	s_cmp_eq_u32 s89, 12
	s_cselect_b32 s75, s26, s41
	s_cselect_b32 s74, s27, s40
	s_cselect_b32 s41, s23, s79
	s_cselect_b32 s40, s69, s78
	s_add_i32 s44, 0, 0x15400
	v_lshl_add_u64 v[198:199], s[38:39], 0, v[168:169]
	s_add_i32 m0, s0, 0xcc00
	global_load_lds_dwordx4 v[198:199], off
	v_lshl_add_u64 v[198:199], s[38:39], 0, v[170:171]
	s_add_i32 m0, s0, 0xee00
	s_nop 0
	global_load_lds_dwordx4 v[198:199], off
	s_waitcnt vmcnt(8)
	s_waitcnt lgkmcnt(0)
	s_barrier
	s_setprio 1
	s_waitcnt lgkmcnt(0)
	v_mfma_f32_16x16x32_bf16 v[140:143], v[48:51], v[172:175], 0
	v_mfma_f32_16x16x32_bf16 v[136:139], v[56:59], v[172:175], 0
	v_mfma_f32_16x16x32_bf16 v[124:127], v[48:51], v[180:183], 0
	v_mfma_f32_16x16x32_bf16 v[120:123], v[56:59], v[180:183], 0
	v_mfma_f32_16x16x32_bf16 v[108:111], v[48:51], v[188:191], 0
	v_mfma_f32_16x16x32_bf16 v[104:107], v[56:59], v[188:191], 0
	v_mfma_f32_16x16x32_bf16 v[92:95], v[48:51], v[212:215], 0
	v_mfma_f32_16x16x32_bf16 v[88:91], v[56:59], v[212:215], 0
	v_mfma_f32_16x16x32_bf16 v[140:143], v[52:55], v[176:179], v[140:143]
	v_mfma_f32_16x16x32_bf16 v[136:139], v[60:63], v[176:179], v[136:139]
	v_mfma_f32_16x16x32_bf16 v[124:127], v[52:55], v[184:187], v[124:127]
	v_mfma_f32_16x16x32_bf16 v[120:123], v[60:63], v[184:187], v[120:123]
	v_mfma_f32_16x16x32_bf16 v[108:111], v[52:55], v[208:211], v[108:111]
	v_mfma_f32_16x16x32_bf16 v[104:107], v[60:63], v[208:211], v[104:107]
	v_mfma_f32_16x16x32_bf16 v[92:95], v[52:55], v[218:221], v[92:95]
	v_mfma_f32_16x16x32_bf16 v[88:91], v[60:63], v[218:221], v[88:91]
	s_setprio 0
	s_setprio 1
	v_mfma_f32_16x16x32_bf16 v[132:135], v[144:147], v[172:175], 0
	v_mfma_f32_16x16x32_bf16 v[128:131], v[152:155], v[172:175], 0
	v_mfma_f32_16x16x32_bf16 v[116:119], v[144:147], v[180:183], 0
	v_mfma_f32_16x16x32_bf16 v[112:115], v[152:155], v[180:183], 0
	v_mfma_f32_16x16x32_bf16 v[100:103], v[144:147], v[188:191], 0
	v_mfma_f32_16x16x32_bf16 v[96:99], v[152:155], v[188:191], 0
	v_mfma_f32_16x16x32_bf16 v[84:87], v[144:147], v[212:215], 0
	v_mfma_f32_16x16x32_bf16 v[80:83], v[152:155], v[212:215], 0
	v_mfma_f32_16x16x32_bf16 v[132:135], v[148:151], v[176:179], v[132:135]
	v_mfma_f32_16x16x32_bf16 v[128:131], v[156:159], v[176:179], v[128:131]
	v_mfma_f32_16x16x32_bf16 v[116:119], v[148:151], v[184:187], v[116:119]
	v_mfma_f32_16x16x32_bf16 v[112:115], v[156:159], v[184:187], v[112:115]
	v_mfma_f32_16x16x32_bf16 v[100:103], v[148:151], v[208:211], v[100:103]
	v_mfma_f32_16x16x32_bf16 v[96:99], v[156:159], v[208:211], v[96:99]
	v_mfma_f32_16x16x32_bf16 v[84:87], v[148:151], v[218:221], v[84:87]
	v_mfma_f32_16x16x32_bf16 v[80:83], v[156:159], v[218:221], v[80:83]
	s_setprio 0
	s_barrier
	s_add_i32 s45, s95, s33
	v_lshl_add_u64 v[198:199], s[40:41], 0, v[192:193]
	s_mov_b32 m0, s45
	ds_read_b128 v[172:175], v217 offset:17408
	ds_read_b128 v[176:179], v217 offset:17472
	ds_read_b128 v[180:183], v217 offset:19584
	ds_read_b128 v[184:187], v217 offset:19648
	ds_read_b128 v[188:191], v217 offset:21760
	ds_read_b128 v[208:211], v217 offset:21824
	ds_read_b128 v[212:215], v217 offset:23936
	ds_read_b128 v[218:221], v217 offset:24000
	global_load_lds_dwordx4 v[198:199], off
	s_add_i32 m0, s45, 0x2200
	s_add_u32 vcc_lo, s40, 0x40000
	v_lshl_add_u64 v[200:201], s[40:41], 0, v[160:161]
	s_addc_u32 vcc_hi, s41, 0
	s_add_i32 s44, s44, s33
	global_load_lds_dwordx4 v[200:201], off
	v_lshl_add_u64 v[222:223], vcc, 0, v[192:193]
	s_mov_b32 m0, s44
	v_lshl_add_u64 v[224:225], s[74:75], 0, v[162:163]
	global_load_lds_dwordx4 v[222:223], off
	v_lshl_add_u64 v[222:223], vcc, 0, v[160:161]
	s_add_i32 m0, s44, 0x2200
	s_nop 0
	global_load_lds_dwordx4 v[222:223], off
	v_lshl_add_u64 v[222:223], s[74:75], 0, v[164:165]
	s_mov_b32 m0, s0
	s_nop 0
	global_load_lds_dwordx4 v[222:223], off
	s_mov_b32 m0, s5
	s_nop 0
	global_load_lds_dwordx4 v[224:225], off
	s_waitcnt vmcnt(8)
	s_waitcnt lgkmcnt(0)
	s_barrier
	s_setprio 1
	s_waitcnt lgkmcnt(0)
	v_mfma_f32_16x16x32_bf16 v[76:79], v[48:51], v[172:175], 0
	v_mfma_f32_16x16x32_bf16 v[72:75], v[56:59], v[172:175], 0
	v_mfma_f32_16x16x32_bf16 v[44:47], v[48:51], v[180:183], 0
	v_mfma_f32_16x16x32_bf16 v[40:43], v[56:59], v[180:183], 0
	v_mfma_f32_16x16x32_bf16 v[24:27], v[48:51], v[188:191], 0
	v_mfma_f32_16x16x32_bf16 v[28:31], v[56:59], v[188:191], 0
	v_mfma_f32_16x16x32_bf16 v[4:7], v[48:51], v[212:215], 0
	v_mfma_f32_16x16x32_bf16 v[12:15], v[56:59], v[212:215], 0
	v_mfma_f32_16x16x32_bf16 v[76:79], v[52:55], v[176:179], v[76:79]
	v_mfma_f32_16x16x32_bf16 v[72:75], v[60:63], v[176:179], v[72:75]
	v_mfma_f32_16x16x32_bf16 v[44:47], v[52:55], v[184:187], v[44:47]
	v_mfma_f32_16x16x32_bf16 v[40:43], v[60:63], v[184:187], v[40:43]
	v_mfma_f32_16x16x32_bf16 v[24:27], v[52:55], v[208:211], v[24:27]
	v_mfma_f32_16x16x32_bf16 v[28:31], v[60:63], v[208:211], v[28:31]
	v_mfma_f32_16x16x32_bf16 v[4:7], v[52:55], v[218:221], v[4:7]
	v_mfma_f32_16x16x32_bf16 v[12:15], v[60:63], v[218:221], v[12:15]
	s_setprio 0
	s_setprio 1
	v_mfma_f32_16x16x32_bf16 v[36:39], v[144:147], v[180:183], 0
	v_mfma_f32_16x16x32_bf16 v[32:35], v[152:155], v[180:183], 0
	v_mfma_f32_16x16x32_bf16 v[20:23], v[144:147], v[188:191], 0
	v_mfma_f32_16x16x32_bf16 v[16:19], v[152:155], v[188:191], 0
	v_mfma_f32_16x16x32_bf16 v[8:11], v[144:147], v[212:215], 0
	v_mfma_f32_16x16x32_bf16 v[0:3], v[152:155], v[212:215], 0
	v_mfma_f32_16x16x32_bf16 v[48:51], v[144:147], v[172:175], 0
	v_mfma_f32_16x16x32_bf16 v[52:55], v[152:155], v[172:175], 0
	v_mfma_f32_16x16x32_bf16 v[36:39], v[148:151], v[184:187], v[36:39]
	v_mfma_f32_16x16x32_bf16 v[32:35], v[156:159], v[184:187], v[32:35]
	v_mfma_f32_16x16x32_bf16 v[20:23], v[148:151], v[208:211], v[20:23]
	v_mfma_f32_16x16x32_bf16 v[16:19], v[156:159], v[208:211], v[16:19]
	v_mfma_f32_16x16x32_bf16 v[8:11], v[148:151], v[218:221], v[8:11]
	v_mfma_f32_16x16x32_bf16 v[0:3], v[156:159], v[218:221], v[0:3]
	v_mfma_f32_16x16x32_bf16 v[48:51], v[148:151], v[176:179], v[48:51]
	v_mfma_f32_16x16x32_bf16 v[52:55], v[156:159], v[176:179], v[52:55]
	s_setprio 0
	s_barrier
; #define PG8_STAGE(bufoff, gbase, voff) do { _Pragma("unroll") for (int _i = 0; _i < 2; ++_i) \
;         __builtin_amdgcn_global_load_lds((const unsigned*)((const char*)(gbase) + (voff)[_i]), (PG8_LAS unsigned*)(lds + (bufoff) + ldsw + _i * (8 * USTR)), 16, 0, 0); } while (0)
; #define PG8_LDA(dst, b, h) do { _Pragma("unroll") for (int m = 0; m < 4; ++m) _Pragma("unroll") for (int k = 0; k < 2; ++k) dst[m][k] = *(const PG8_LAS bf16x8*)(lds + PG8_SA(b, h) + aoff + m * (2 * USTR) + k * 64); } while (0)
; #define PG8_LDB(dst, b, h) do { _Pragma("unroll") for (int n = 0; n < 2; ++n) _Pragma("unroll") for (int k = 0; k < 2; ++k) dst[n][k] = *(const PG8_LAS bf16x8*)(lds + PG8_SB(b, h) + boff + n * (2 * USTR) + k * 64); } while (0)
; #define PG8_MMA(ai, bj, At, Bt) do { __builtin_amdgcn_s_setprio(1); _Pragma("unroll") for (int m = 0; m < 4; ++m) _Pragma("unroll") for (int n = 0; n < 2; ++n) _Pragma("unroll") for (int k = 0; k < 2; ++k) \
;         acc[ai][bj][m][n] = __builtin_amdgcn_mfma_f32_16x16x32_bf16(Bt[n][k], At[m][k], acc[ai][bj][m][n], 0, 0, 0); __builtin_amdgcn_s_setprio(0); } while (0)
; #define PG8_WAIT_V(n) asm volatile("s_waitcnt vmcnt(" #n ")" ::: "memory")
; #define PG8_WAIT_L(n) asm volatile("s_waitcnt lgkmcnt(" #n ")" ::: "memory")
; #define PG8_BAR __builtin_amdgcn_s_barrier()
; #define PG8_SCHED __builtin_amdgcn_sched_barrier(0)
; template <class Epi, class Sched, bool ALIGN_EPI, bool SP2>
; __device__ __forceinline__ void gemm_phase(PG8_LAS unsigned char* lds, const Gemm g, const Sched& S, const Epi& E, int wid) {
;     ...
;             PG8_LDB(B0, 1, 0); PG8_LDB(B1, 1, 1); PG8_SCHED; PG8_LDA(At, 1, 0); PG8_STAGE(PG8_SA(0, 1), a2 + hstepA, voffA);
;             PG8_WAIT_V(8); PG8_WAIT_L(0); PG8_BAR; PG8_MMA(0, 0, At, B0); PG8_MMA(0, 1, At, B1); PG8_BAR; PG8_SCHED;
	s_add_i32 s44, 0, 0x19800
	s_add_i32 s45, 0, 0x1dc00
	v_add_u32_e32 v68, s44, v216
	v_add_u32_e32 v156, s45, v216
	ds_read_b128 v[56:59], v68
	ds_read_b128 v[60:63], v68 offset:64
	ds_read_b128 v[64:67], v68 offset:2176
	ds_read_b128 v[68:71], v68 offset:2240
	ds_read_b128 v[144:147], v156
	ds_read_b128 v[148:151], v156 offset:64
	ds_read_b128 v[152:155], v156 offset:2176
	ds_read_b128 v[156:159], v156 offset:2240
	s_add_u32 s74, s74, 0x80000
	s_addc_u32 s75, s75, 0
	s_mov_b32 m0, s29
	v_lshl_add_u64 v[226:227], s[74:75], 0, v[164:165]
	ds_read_b128 v[172:175], v217 offset:34816
	ds_read_b128 v[176:179], v217 offset:34880
	ds_read_b128 v[180:183], v217 offset:36992
	ds_read_b128 v[184:187], v217 offset:37056
	ds_read_b128 v[188:191], v217 offset:39168
	ds_read_b128 v[208:211], v217 offset:39232
	ds_read_b128 v[212:215], v217 offset:41344
	ds_read_b128 v[218:221], v217 offset:41408
	global_load_lds_dwordx4 v[226:227], off
	v_lshl_add_u64 v[226:227], s[74:75], 0, v[162:163]
	s_mov_b32 m0, s56
	s_nop 0
	global_load_lds_dwordx4 v[226:227], off
	s_waitcnt vmcnt(8)
	s_waitcnt lgkmcnt(0)
	s_barrier
	s_setprio 1
	s_waitcnt lgkmcnt(0)
	v_mfma_f32_16x16x32_bf16 v[140:143], v[56:59], v[172:175], v[140:143]
	v_mfma_f32_16x16x32_bf16 v[136:139], v[64:67], v[172:175], v[136:139]
	v_mfma_f32_16x16x32_bf16 v[124:127], v[56:59], v[180:183], v[124:127]
	v_mfma_f32_16x16x32_bf16 v[120:123], v[64:67], v[180:183], v[120:123]
	v_mfma_f32_16x16x32_bf16 v[108:111], v[56:59], v[188:191], v[108:111]
	v_mfma_f32_16x16x32_bf16 v[104:107], v[64:67], v[188:191], v[104:107]
	v_mfma_f32_16x16x32_bf16 v[92:95], v[56:59], v[212:215], v[92:95]
	v_mfma_f32_16x16x32_bf16 v[88:91], v[64:67], v[212:215], v[88:91]
	v_mfma_f32_16x16x32_bf16 v[140:143], v[60:63], v[176:179], v[140:143]
	v_mfma_f32_16x16x32_bf16 v[136:139], v[68:71], v[176:179], v[136:139]
	v_mfma_f32_16x16x32_bf16 v[124:127], v[60:63], v[184:187], v[124:127]
	v_mfma_f32_16x16x32_bf16 v[120:123], v[68:71], v[184:187], v[120:123]
	v_mfma_f32_16x16x32_bf16 v[108:111], v[60:63], v[208:211], v[108:111]
	v_mfma_f32_16x16x32_bf16 v[104:107], v[68:71], v[208:211], v[104:107]
	v_mfma_f32_16x16x32_bf16 v[92:95], v[60:63], v[218:221], v[92:95]
	v_mfma_f32_16x16x32_bf16 v[88:91], v[68:71], v[218:221], v[88:91]
	s_setprio 0
	s_setprio 1
	v_mfma_f32_16x16x32_bf16 v[132:135], v[144:147], v[172:175], v[132:135]
	v_mfma_f32_16x16x32_bf16 v[128:131], v[152:155], v[172:175], v[128:131]
	v_mfma_f32_16x16x32_bf16 v[116:119], v[144:147], v[180:183], v[116:119]
	v_mfma_f32_16x16x32_bf16 v[112:115], v[152:155], v[180:183], v[112:115]
	v_mfma_f32_16x16x32_bf16 v[100:103], v[144:147], v[188:191], v[100:103]
	v_mfma_f32_16x16x32_bf16 v[96:99], v[152:155], v[188:191], v[96:99]
	v_mfma_f32_16x16x32_bf16 v[84:87], v[144:147], v[212:215], v[84:87]
	v_mfma_f32_16x16x32_bf16 v[80:83], v[152:155], v[212:215], v[80:83]
	v_mfma_f32_16x16x32_bf16 v[132:135], v[148:151], v[176:179], v[132:135]
	v_mfma_f32_16x16x32_bf16 v[128:131], v[156:159], v[176:179], v[128:131]
	v_mfma_f32_16x16x32_bf16 v[116:119], v[148:151], v[184:187], v[116:119]
	v_mfma_f32_16x16x32_bf16 v[112:115], v[156:159], v[184:187], v[112:115]
	v_mfma_f32_16x16x32_bf16 v[100:103], v[148:151], v[208:211], v[100:103]
	v_mfma_f32_16x16x32_bf16 v[96:99], v[156:159], v[208:211], v[96:99]
	v_mfma_f32_16x16x32_bf16 v[84:87], v[148:151], v[218:221], v[84:87]
	v_mfma_f32_16x16x32_bf16 v[80:83], v[156:159], v[218:221], v[80:83]
	s_setprio 0
	s_barrier
; #define PG8_STAGE(bufoff, gbase, voff) do { _Pragma("unroll") for (int _i = 0; _i < 2; ++_i) \
;         __builtin_amdgcn_global_load_lds((const unsigned*)((const char*)(gbase) + (voff)[_i]), (PG8_LAS unsigned*)(lds + (bufoff) + ldsw + _i * (8 * USTR)), 16, 0, 0); } while (0)
; #define PG8_LDA(dst, b, h) do { _Pragma("unroll") for (int m = 0; m < 4; ++m) _Pragma("unroll") for (int k = 0; k < 2; ++k) dst[m][k] = *(const PG8_LAS bf16x8*)(lds + PG8_SA(b, h) + aoff + m * (2 * USTR) + k * 64); } while (0)
; #define PG8_MMA(ai, bj, At, Bt) do { __builtin_amdgcn_s_setprio(1); _Pragma("unroll") for (int m = 0; m < 4; ++m) _Pragma("unroll") for (int n = 0; n < 2; ++n) _Pragma("unroll") for (int k = 0; k < 2; ++k) \
;         acc[ai][bj][m][n] = __builtin_amdgcn_mfma_f32_16x16x32_bf16(Bt[n][k], At[m][k], acc[ai][bj][m][n], 0, 0, 0); __builtin_amdgcn_s_setprio(0); } while (0)
; #define PG8_WAIT_V(n) asm volatile("s_waitcnt vmcnt(" #n ")" ::: "memory")
; #define PG8_WAIT_L(n) asm volatile("s_waitcnt lgkmcnt(" #n ")" ::: "memory")
; #define PG8_BAR __builtin_amdgcn_s_barrier()
; #define PG8_SCHED __builtin_amdgcn_sched_barrier(0)
; template <class Epi, class Sched, bool ALIGN_EPI, bool SP2>
; __device__ __forceinline__ void gemm_phase(PG8_LAS unsigned char* lds, const Gemm g, const Sched& S, const Epi& E, int wid) {
;     ...
;             PG8_LDA(At, 1, 1); PG8_STAGE(PG8_SB(1, 0), b3, voffB); PG8_STAGE(PG8_SB(1, 1), b3 + hstepB, voffB); PG8_STAGE(PG8_SA(1, 0), a3, voffA);
;             PG8_WAIT_V(8); PG8_WAIT_L(0); PG8_BAR; PG8_MMA(1, 0, At, B0); PG8_MMA(1, 1, At, B1); PG8_BAR; PG8_SCHED;
	s_add_i32 s44, s44, s33
	v_lshl_add_u64 v[198:199], v[198:199], 0, s[6:7]
	s_mov_b32 m0, s44
	ds_read_b128 v[172:175], v217 offset:52224
	ds_read_b128 v[176:179], v217 offset:52288
	ds_read_b128 v[180:183], v217 offset:54400
	ds_read_b128 v[184:187], v217 offset:54464
	ds_read_b128 v[188:191], v217 offset:56576
	ds_read_b128 v[208:211], v217 offset:56640
	ds_read_b128 v[212:215], v217 offset:58752
	ds_read_b128 v[218:221], v217 offset:58816
	global_load_lds_dwordx4 v[198:199], off
	s_add_i32 m0, s44, 0x2200
	s_add_u32 s40, s40, 0x40080
	v_lshl_add_u64 v[198:199], v[200:201], 0, s[6:7]
	s_addc_u32 s41, s41, 0
	s_add_i32 s44, s45, s33
	global_load_lds_dwordx4 v[198:199], off
	v_lshl_add_u64 v[198:199], s[40:41], 0, v[192:193]
	s_mov_b32 m0, s44
	s_nop 0
	global_load_lds_dwordx4 v[198:199], off
	v_lshl_add_u64 v[198:199], s[40:41], 0, v[160:161]
	s_add_i32 m0, s44, 0x2200
	s_nop 0
	global_load_lds_dwordx4 v[198:199], off
	v_lshl_add_u64 v[198:199], v[222:223], 0, s[6:7]
	s_mov_b32 m0, s57
	s_nop 0
	global_load_lds_dwordx4 v[198:199], off
	v_lshl_add_u64 v[198:199], v[224:225], 0, s[6:7]
	s_mov_b32 m0, s76
	s_nop 0
	global_load_lds_dwordx4 v[198:199], off
	s_waitcnt vmcnt(8)
	s_waitcnt lgkmcnt(0)
	s_barrier
	s_setprio 1
	s_waitcnt lgkmcnt(0)
	v_mfma_f32_16x16x32_bf16 v[76:79], v[56:59], v[172:175], v[76:79]
	v_mfma_f32_16x16x32_bf16 v[72:75], v[64:67], v[172:175], v[72:75]
	v_mfma_f32_16x16x32_bf16 v[44:47], v[56:59], v[180:183], v[44:47]
	v_mfma_f32_16x16x32_bf16 v[40:43], v[64:67], v[180:183], v[40:43]
	v_mfma_f32_16x16x32_bf16 v[24:27], v[56:59], v[188:191], v[24:27]
	v_mfma_f32_16x16x32_bf16 v[28:31], v[64:67], v[188:191], v[28:31]
	v_mfma_f32_16x16x32_bf16 v[4:7], v[56:59], v[212:215], v[4:7]
	v_mfma_f32_16x16x32_bf16 v[12:15], v[64:67], v[212:215], v[12:15]
	v_mfma_f32_16x16x32_bf16 v[76:79], v[60:63], v[176:179], v[76:79]
	v_mfma_f32_16x16x32_bf16 v[72:75], v[68:71], v[176:179], v[72:75]
	v_mfma_f32_16x16x32_bf16 v[44:47], v[60:63], v[184:187], v[44:47]
	v_mfma_f32_16x16x32_bf16 v[40:43], v[68:71], v[184:187], v[40:43]
	v_mfma_f32_16x16x32_bf16 v[24:27], v[60:63], v[208:211], v[24:27]
	v_mfma_f32_16x16x32_bf16 v[28:31], v[68:71], v[208:211], v[28:31]
	v_mfma_f32_16x16x32_bf16 v[4:7], v[60:63], v[218:221], v[4:7]
	v_mfma_f32_16x16x32_bf16 v[12:15], v[68:71], v[218:221], v[12:15]
	s_setprio 0
	s_setprio 1
	v_mfma_f32_16x16x32_bf16 v[48:51], v[144:147], v[172:175], v[48:51]
	v_mfma_f32_16x16x32_bf16 v[68:71], v[148:151], v[176:179], v[48:51]
	v_mfma_f32_16x16x32_bf16 v[48:51], v[152:155], v[172:175], v[52:55]
	v_mfma_f32_16x16x32_bf16 v[36:39], v[144:147], v[180:183], v[36:39]
	v_mfma_f32_16x16x32_bf16 v[32:35], v[152:155], v[180:183], v[32:35]
	v_mfma_f32_16x16x32_bf16 v[20:23], v[144:147], v[188:191], v[20:23]
	v_mfma_f32_16x16x32_bf16 v[16:19], v[152:155], v[188:191], v[16:19]
	v_mfma_f32_16x16x32_bf16 v[8:11], v[144:147], v[212:215], v[8:11]
	v_mfma_f32_16x16x32_bf16 v[0:3], v[152:155], v[212:215], v[0:3]
	v_mfma_f32_16x16x32_bf16 v[64:67], v[156:159], v[176:179], v[48:51]
	v_mfma_f32_16x16x32_bf16 v[36:39], v[148:151], v[184:187], v[36:39]
	v_mfma_f32_16x16x32_bf16 v[32:35], v[156:159], v[184:187], v[32:35]
	v_mfma_f32_16x16x32_bf16 v[20:23], v[148:151], v[208:211], v[20:23]
	v_mfma_f32_16x16x32_bf16 v[16:19], v[156:159], v[208:211], v[16:19]
	v_mfma_f32_16x16x32_bf16 v[8:11], v[148:151], v[218:221], v[8:11]
	v_mfma_f32_16x16x32_bf16 v[0:3], v[156:159], v[218:221], v[0:3]
	s_setprio 0
	s_barrier
	s_add_i32 s89, s89, 2
	s_add_u32 s38, s38, 0x100
	s_addc_u32 s39, s39, 0
	s_add_u32 s78, s78, 0x100
	s_addc_u32 s79, s79, 0
	s_cmp_gt_u32 s89, 13

; #define PG8_STAGE(bufoff, gbase, voff) do { _Pragma("unroll") for (int _i = 0; _i < 2; ++_i) \
;         __builtin_amdgcn_global_load_lds((const unsigned*)((const char*)(gbase) + (voff)[_i]), (PG8_LAS unsigned*)(lds + (bufoff) + ldsw + _i * (8 * USTR)), 16, 0, 0); } while (0)
; #define PG8_LDA(dst, b, h) do { _Pragma("unroll") for (int m = 0; m < 4; ++m) _Pragma("unroll") for (int k = 0; k < 2; ++k) dst[m][k] = *(const PG8_LAS bf16x8*)(lds + PG8_SA(b, h) + aoff + m * (2 * USTR) + k * 64); } while (0)
; #define PG8_LDB(dst, b, h) do { _Pragma("unroll") for (int n = 0; n < 2; ++n) _Pragma("unroll") for (int k = 0; k < 2; ++k) dst[n][k] = *(const PG8_LAS bf16x8*)(lds + PG8_SB(b, h) + boff + n * (2 * USTR) + k * 64); } while (0)
; #define PG8_SCHED __builtin_amdgcn_sched_barrier(0)
;     __host__ __device__ bool next(int i, Unit& u) const {
;         const long L = (long)i * G + c; if (L >= nwg) return false;
;         int wgid = (int)L; { const int q = nwg / NXCD, r = nwg % NXCD, xcd = wgid % NXCD, off = wgid / NXCD; wgid = (xcd < r ? xcd * (q + 1) : r * (q + 1) + (xcd - r) * q) + off; }
;         const int nig = WGM * nN, gid = wgid / nig, fm = gid * WGM, gsz = (nM - fm) < WGM ? (nM - fm) : WGM;
;         u.pm = fm + ((wgid % nig) % gsz); u.pn = (wgid % nig) / gsz; return true;
; template <class Epi, class Sched, bool ALIGN_EPI, bool SP2>
; __device__ __forceinline__ void gemm_phase(PG8_LAS unsigned char* lds, const Gemm g, const Sched& S, const Epi& E, int wid) {
;     ...
;             PG8_LDB(B0, 0, 0); PG8_LDB(B1, 0, 1); PG8_SCHED; PG8_LDA(At, 0, 0); PG8_STAGE(PG8_SA(1, 1), a1 + hstepA, voffA);
.LBB0_279:
	s_add_i32 s69, 0, 0x11000
	s_add_i32 s76, 0, 0x15400
	v_add_u32_e32 v52, s69, v197
	v_add_u32_e32 v156, s76, v197
	ds_read_b128 v[40:43], v52
	ds_read_b128 v[44:47], v52 offset:64
	ds_read_b128 v[48:51], v52 offset:2176
	ds_read_b128 v[52:55], v52 offset:2240
	ds_read_b128 v[144:147], v156
	ds_read_b128 v[148:151], v156 offset:64
	ds_read_b128 v[152:155], v156 offset:2176
	ds_read_b128 v[156:159], v156 offset:2240
	ds_read_b128 v[160:163], v241
	ds_read_b128 v[164:167], v241 offset:64
	ds_read_b128 v[168:171], v241 offset:2176
	ds_read_b128 v[172:175], v241 offset:2240
	ds_read_b128 v[176:179], v241 offset:4352
	ds_read_b128 v[180:183], v241 offset:4416
	ds_read_b128 v[184:187], v241 offset:6528
	ds_read_b128 v[188:191], v241 offset:6592
	s_add_i32 s71, s71, 1
	s_mul_i32 s22, s71, s13
	s_mul_hi_u32 s23, s71, s3
	s_add_i32 s23, s23, s22
	s_mul_i32 s22, s71, s3
	v_readlane_b32 s26, v251, 0
	s_add_u32 s22, s22, s26
	s_addc_u32 s23, s23, s58
	s_waitcnt lgkmcnt(0)
	v_mov_b64_e32 v[0:1], 0x200
	v_cmp_gt_i64_e32 vcc, s[22:23], v[238:239]
	v_cmp_lt_i64_e64 s[38:39], s[22:23], v[0:1]
	s_cbranch_vccnz .LBB0_285
	s_ashr_i32 s23, s22, 31
	s_lshr_b32 s23, s23, 29
	s_add_i32 s26, s22, s23
	s_and_b32 s23, s26, -8
	s_sub_i32 s27, s22, s23
	s_cmp_gt_i32 s27, -1
	s_mov_b64 s[22:23], -1
	s_cbranch_scc0 .LBB0_282
	s_lshl_b32 s36, s27, 6
	s_mov_b64 s[22:23], 0

; #define PG8_LAS __attribute__((address_space(3)))
; #define PG8_STAGE(bufoff, gbase, voff) do { _Pragma("unroll") for (int _i = 0; _i < 2; ++_i) \
;         __builtin_amdgcn_global_load_lds((const unsigned*)((const char*)(gbase) + (voff)[_i]), (PG8_LAS unsigned*)(lds + (bufoff) + ldsw + _i * (8 * USTR)), 16, 0, 0); } while (0)
; #define PG8_LDA(dst, b, h) do { _Pragma("unroll") for (int m = 0; m < 4; ++m) _Pragma("unroll") for (int k = 0; k < 2; ++k) dst[m][k] = *(const PG8_LAS bf16x8*)(lds + PG8_SA(b, h) + aoff + m * (2 * USTR) + k * 64); } while (0)
; template <class Epi, class Sched, bool ALIGN_EPI, bool SP2>
; __device__ __forceinline__ void gemm_phase(PG8_LAS unsigned char* lds, const Gemm g, const Sched& S, const Epi& E, int wid) {
;     ...
;         const char* nA = has_next ? (const char*)g.A + (size_t)nxt.pm * tstepA : cA; const char* nB = has_next ? (const char*)g.Bt + (size_t)nxt.pn * tstepB : cB;
;         for (int t = 0; t < nt; t += 2) {
;             const bool last = (t == nt - 2);
;             const char* a1 = cA + (size_t)(t + 1) * kstep;
;             const char* a2 = last ? nA : cA + (size_t)(t + 2) * kstep; const char* b2 = last ? nB : cB + (size_t)(t + 2) * kstep;
;             const char* a3 = a2 + kstep; const char* b3 = b2 + kstep;
;             if constexpr (Epi::PRE == 1) { if (last) {
;                 const char* rsrc; const char* ssrc; E.pre(cur, rsrc, ssrc);
; #pragma unroll
;                 for (int _i = 0; _i < 2; ++_i) __builtin_amdgcn_global_load_lds((const unsigned*)(rsrc + (wid + 8 * _i) * 1024 + lane * 16), (PG8_LAS unsigned*)(lds + LDS_XOFF + (wid + 8 * _i) * 1024), 16, 0, 0);
;                 if (wid == 0) __builtin_amdgcn_global_load_lds((const unsigned*)(ssrc + lane * 16), (PG8_LAS unsigned*)(lds + LDS_XOFF + 16384), 16, 0, 0);
;             } }
;             if constexpr (SP2) {
;             PG8_LDB(B0, 0, 0); PG8_LDB(B1, 0, 1); PG8_SCHED; PG8_LDA(At, 0, 0); PG8_STAGE(PG8_SA(1, 1), a1 + hstepA, voffA);
;             PG8_WAIT_V(8); PG8_WAIT_L(0); PG8_BAR; PG8_MMA(0, 0, At, B0); PG8_MMA(0, 1, At, B1); PG8_BAR; PG8_SCHED;
;             PG8_LDA(At, 0, 1); PG8_STAGE(PG8_SB(0, 0), b2, voffB); PG8_STAGE(PG8_SB(0, 1), b2 + hstepB, voffB); PG8_STAGE(PG8_SA(0, 0), a2, voffA);
;             PG8_WAIT_V(8); PG8_WAIT_L(0); PG8_BAR; PG8_MMA(1, 0, At, B0); PG8_MMA(1, 1, At, B1); PG8_BAR; PG8_SCHED;
.Lhb_down:
	s_add_u32 s40, s38, 0xfff50080
	s_addc_u32 s41, s39, -1
	s_add_i32 s69, 0, 0x11000
	s_cmp_eq_u32 s68, 40
	s_cselect_b32 s43, s23, s41
	s_cselect_b32 s42, s22, s40
	s_cselect_b32 s41, s45, s27
	s_cselect_b32 s40, s44, s26
	s_add_i32 s76, 0, 0x15400
	v_lshl_add_u64 v[198:199], s[38:39], 0, v[212:213]
	s_add_i32 m0, s0, 0xcc00
	global_load_lds_dwordx4 v[198:199], off
	v_lshl_add_u64 v[198:199], s[38:39], 0, v[214:215]
	s_add_i32 m0, s0, 0xee00
	s_nop 0
	global_load_lds_dwordx4 v[198:199], off
	s_waitcnt vmcnt(8)
	s_waitcnt lgkmcnt(0)
	s_barrier
	s_setprio 1
	s_waitcnt lgkmcnt(0)
	v_mfma_f32_16x16x32_bf16 v[132:135], v[40:43], v[160:163], 0
	v_mfma_f32_16x16x32_bf16 v[128:131], v[48:51], v[160:163], 0
	v_mfma_f32_16x16x32_bf16 v[124:127], v[40:43], v[168:171], 0
	v_mfma_f32_16x16x32_bf16 v[120:123], v[48:51], v[168:171], 0
	v_mfma_f32_16x16x32_bf16 v[108:111], v[40:43], v[176:179], 0
	v_mfma_f32_16x16x32_bf16 v[104:107], v[48:51], v[176:179], 0
	v_mfma_f32_16x16x32_bf16 v[92:95], v[40:43], v[184:187], 0
	v_mfma_f32_16x16x32_bf16 v[88:91], v[48:51], v[184:187], 0
	v_mfma_f32_16x16x32_bf16 v[132:135], v[44:47], v[164:167], v[132:135]
	v_mfma_f32_16x16x32_bf16 v[128:131], v[52:55], v[164:167], v[128:131]
	v_mfma_f32_16x16x32_bf16 v[124:127], v[44:47], v[172:175], v[124:127]
	v_mfma_f32_16x16x32_bf16 v[120:123], v[52:55], v[172:175], v[120:123]
	v_mfma_f32_16x16x32_bf16 v[108:111], v[44:47], v[180:183], v[108:111]
	v_mfma_f32_16x16x32_bf16 v[104:107], v[52:55], v[180:183], v[104:107]
	v_mfma_f32_16x16x32_bf16 v[92:95], v[44:47], v[188:191], v[92:95]
	v_mfma_f32_16x16x32_bf16 v[88:91], v[52:55], v[188:191], v[88:91]
	s_setprio 0
	s_setprio 1
	v_mfma_f32_16x16x32_bf16 v[140:143], v[144:147], v[160:163], 0
	v_mfma_f32_16x16x32_bf16 v[136:139], v[152:155], v[160:163], 0
	v_mfma_f32_16x16x32_bf16 v[116:119], v[144:147], v[168:171], 0
	v_mfma_f32_16x16x32_bf16 v[112:115], v[152:155], v[168:171], 0
	v_mfma_f32_16x16x32_bf16 v[100:103], v[144:147], v[176:179], 0
	v_mfma_f32_16x16x32_bf16 v[96:99], v[152:155], v[176:179], 0
	v_mfma_f32_16x16x32_bf16 v[84:87], v[144:147], v[184:187], 0
	v_mfma_f32_16x16x32_bf16 v[80:83], v[152:155], v[184:187], 0
	v_mfma_f32_16x16x32_bf16 v[140:143], v[148:151], v[164:167], v[140:143]
	v_mfma_f32_16x16x32_bf16 v[136:139], v[156:159], v[164:167], v[136:139]
	v_mfma_f32_16x16x32_bf16 v[116:119], v[148:151], v[172:175], v[116:119]
	v_mfma_f32_16x16x32_bf16 v[112:115], v[156:159], v[172:175], v[112:115]
	v_mfma_f32_16x16x32_bf16 v[100:103], v[148:151], v[180:183], v[100:103]
	v_mfma_f32_16x16x32_bf16 v[96:99], v[156:159], v[180:183], v[96:99]
	v_mfma_f32_16x16x32_bf16 v[84:87], v[148:151], v[188:191], v[84:87]
	v_mfma_f32_16x16x32_bf16 v[80:83], v[156:159], v[188:191], v[80:83]
	s_setprio 0
	s_barrier
	s_add_i32 s69, s69, s33
	v_lshl_add_u64 v[198:199], s[40:41], 0, v[208:209]
	s_mov_b32 m0, s69
	ds_read_b128 v[160:163], v241 offset:17408
	ds_read_b128 v[164:167], v241 offset:17472
	ds_read_b128 v[168:171], v241 offset:19584
	ds_read_b128 v[172:175], v241 offset:19648
	ds_read_b128 v[176:179], v241 offset:21760
	ds_read_b128 v[180:183], v241 offset:21824
	ds_read_b128 v[184:187], v241 offset:23936
	ds_read_b128 v[188:191], v241 offset:24000
	global_load_lds_dwordx4 v[198:199], off
	s_add_i32 m0, s69, 0x2200
	s_add_u32 s74, s40, 0xb0000
	v_lshl_add_u64 v[200:201], s[40:41], 0, v[210:211]
	s_addc_u32 s75, s41, 0
	s_add_i32 s69, s76, s33
	global_load_lds_dwordx4 v[200:201], off
	v_lshl_add_u64 v[216:217], s[74:75], 0, v[208:209]
	s_mov_b32 m0, s69
	v_lshl_add_u64 v[218:219], s[42:43], 0, v[210:211]
	global_load_lds_dwordx4 v[216:217], off
	v_lshl_add_u64 v[216:217], s[74:75], 0, v[210:211]
	s_add_i32 m0, s69, 0x2200
	s_nop 0
	global_load_lds_dwordx4 v[216:217], off
	v_lshl_add_u64 v[216:217], s[42:43], 0, v[208:209]
	s_mov_b32 m0, s0
	s_nop 0
	global_load_lds_dwordx4 v[216:217], off
	s_mov_b32 m0, s5
	s_nop 0
	global_load_lds_dwordx4 v[218:219], off
	s_waitcnt vmcnt(8)
	s_waitcnt lgkmcnt(0)
	s_barrier
	s_setprio 1
	s_waitcnt lgkmcnt(0)
	v_mfma_f32_16x16x32_bf16 v[76:79], v[40:43], v[160:163], 0
	v_mfma_f32_16x16x32_bf16 v[72:75], v[48:51], v[160:163], 0
	v_mfma_f32_16x16x32_bf16 v[60:63], v[40:43], v[168:171], 0
	v_mfma_f32_16x16x32_bf16 v[56:59], v[48:51], v[168:171], 0
	v_mfma_f32_16x16x32_bf16 v[24:27], v[40:43], v[176:179], 0
	v_mfma_f32_16x16x32_bf16 v[28:31], v[48:51], v[176:179], 0
	v_mfma_f32_16x16x32_bf16 v[8:11], v[40:43], v[184:187], 0
	v_mfma_f32_16x16x32_bf16 v[12:15], v[48:51], v[184:187], 0
	v_mfma_f32_16x16x32_bf16 v[76:79], v[44:47], v[164:167], v[76:79]
	v_mfma_f32_16x16x32_bf16 v[72:75], v[52:55], v[164:167], v[72:75]
	v_mfma_f32_16x16x32_bf16 v[60:63], v[44:47], v[172:175], v[60:63]
	v_mfma_f32_16x16x32_bf16 v[56:59], v[52:55], v[172:175], v[56:59]
	v_mfma_f32_16x16x32_bf16 v[24:27], v[44:47], v[180:183], v[24:27]
	v_mfma_f32_16x16x32_bf16 v[28:31], v[52:55], v[180:183], v[28:31]
	v_mfma_f32_16x16x32_bf16 v[8:11], v[44:47], v[188:191], v[8:11]
	v_mfma_f32_16x16x32_bf16 v[12:15], v[52:55], v[188:191], v[12:15]
	s_setprio 0
	s_setprio 1
	v_mfma_f32_16x16x32_bf16 v[36:39], v[144:147], v[168:171], 0
	v_mfma_f32_16x16x32_bf16 v[32:35], v[152:155], v[168:171], 0
	v_mfma_f32_16x16x32_bf16 v[20:23], v[144:147], v[176:179], 0
	v_mfma_f32_16x16x32_bf16 v[16:19], v[152:155], v[176:179], 0
	v_mfma_f32_16x16x32_bf16 v[4:7], v[144:147], v[184:187], 0
	v_mfma_f32_16x16x32_bf16 v[0:3], v[152:155], v[184:187], 0
	v_mfma_f32_16x16x32_bf16 v[40:43], v[144:147], v[160:163], 0
	v_mfma_f32_16x16x32_bf16 v[44:47], v[152:155], v[160:163], 0
	v_mfma_f32_16x16x32_bf16 v[36:39], v[148:151], v[172:175], v[36:39]
	v_mfma_f32_16x16x32_bf16 v[32:35], v[156:159], v[172:175], v[32:35]
	v_mfma_f32_16x16x32_bf16 v[20:23], v[148:151], v[180:183], v[20:23]
	v_mfma_f32_16x16x32_bf16 v[16:19], v[156:159], v[180:183], v[16:19]
	v_mfma_f32_16x16x32_bf16 v[4:7], v[148:151], v[188:191], v[4:7]
	v_mfma_f32_16x16x32_bf16 v[0:3], v[156:159], v[188:191], v[0:3]
	v_mfma_f32_16x16x32_bf16 v[40:43], v[148:151], v[164:167], v[40:43]
	v_mfma_f32_16x16x32_bf16 v[44:47], v[156:159], v[164:167], v[44:47]
	s_setprio 0
	s_barrier
; #define PG8_STAGE(bufoff, gbase, voff) do { _Pragma("unroll") for (int _i = 0; _i < 2; ++_i) \
;         __builtin_amdgcn_global_load_lds((const unsigned*)((const char*)(gbase) + (voff)[_i]), (PG8_LAS unsigned*)(lds + (bufoff) + ldsw + _i * (8 * USTR)), 16, 0, 0); } while (0)
; #define PG8_LDA(dst, b, h) do { _Pragma("unroll") for (int m = 0; m < 4; ++m) _Pragma("unroll") for (int k = 0; k < 2; ++k) dst[m][k] = *(const PG8_LAS bf16x8*)(lds + PG8_SA(b, h) + aoff + m * (2 * USTR) + k * 64); } while (0)
; #define PG8_LDB(dst, b, h) do { _Pragma("unroll") for (int n = 0; n < 2; ++n) _Pragma("unroll") for (int k = 0; k < 2; ++k) dst[n][k] = *(const PG8_LAS bf16x8*)(lds + PG8_SB(b, h) + boff + n * (2 * USTR) + k * 64); } while (0)
; #define PG8_MMA(ai, bj, At, Bt) do { __builtin_amdgcn_s_setprio(1); _Pragma("unroll") for (int m = 0; m < 4; ++m) _Pragma("unroll") for (int n = 0; n < 2; ++n) _Pragma("unroll") for (int k = 0; k < 2; ++k) \
;         acc[ai][bj][m][n] = __builtin_amdgcn_mfma_f32_16x16x32_bf16(Bt[n][k], At[m][k], acc[ai][bj][m][n], 0, 0, 0); __builtin_amdgcn_s_setprio(0); } while (0)
; #define PG8_WAIT_V(n) asm volatile("s_waitcnt vmcnt(" #n ")" ::: "memory")
; #define PG8_WAIT_L(n) asm volatile("s_waitcnt lgkmcnt(" #n ")" ::: "memory")
; #define PG8_BAR __builtin_amdgcn_s_barrier()
; #define PG8_SCHED __builtin_amdgcn_sched_barrier(0)
; template <class Epi, class Sched, bool ALIGN_EPI, bool SP2>
; __device__ __forceinline__ void gemm_phase(PG8_LAS unsigned char* lds, const Gemm g, const Sched& S, const Epi& E, int wid) {
;     ...
;             PG8_LDB(B0, 1, 0); PG8_LDB(B1, 1, 1); PG8_SCHED; PG8_LDA(At, 1, 0); PG8_STAGE(PG8_SA(0, 1), a2 + hstepA, voffA);
;             PG8_WAIT_V(8); PG8_WAIT_L(0); PG8_BAR; PG8_MMA(0, 0, At, B0); PG8_MMA(0, 1, At, B1); PG8_BAR; PG8_SCHED;
	s_add_i32 s69, 0, 0x19800
	s_add_i32 s74, 0, 0x1dc00
	v_add_u32_e32 v68, s69, v197
	v_add_u32_e32 v156, s74, v197
	ds_read_b128 v[48:51], v68
	ds_read_b128 v[52:55], v68 offset:64
	ds_read_b128 v[64:67], v68 offset:2176
	ds_read_b128 v[68:71], v68 offset:2240
	ds_read_b128 v[144:147], v156
	ds_read_b128 v[148:151], v156 offset:64
	ds_read_b128 v[152:155], v156 offset:2176
	ds_read_b128 v[156:159], v156 offset:2240
	s_add_u32 s42, s42, 0xb0000
	s_addc_u32 s43, s43, 0
	s_mov_b32 m0, s29
	v_lshl_add_u64 v[220:221], s[42:43], 0, v[208:209]
	ds_read_b128 v[160:163], v241 offset:34816
	ds_read_b128 v[164:167], v241 offset:34880
	ds_read_b128 v[168:171], v241 offset:36992
	ds_read_b128 v[172:175], v241 offset:37056
	ds_read_b128 v[176:179], v241 offset:39168
	ds_read_b128 v[180:183], v241 offset:39232
	ds_read_b128 v[184:187], v241 offset:41344
	ds_read_b128 v[188:191], v241 offset:41408
	global_load_lds_dwordx4 v[220:221], off
	v_lshl_add_u64 v[220:221], s[42:43], 0, v[210:211]
	s_mov_b32 m0, s56
	s_nop 0
	global_load_lds_dwordx4 v[220:221], off
	s_waitcnt vmcnt(8)
	s_waitcnt lgkmcnt(0)
	s_barrier
	s_setprio 1
	s_waitcnt lgkmcnt(0)
	v_mfma_f32_16x16x32_bf16 v[132:135], v[48:51], v[160:163], v[132:135]
	v_mfma_f32_16x16x32_bf16 v[128:131], v[64:67], v[160:163], v[128:131]
	v_mfma_f32_16x16x32_bf16 v[124:127], v[48:51], v[168:171], v[124:127]
	v_mfma_f32_16x16x32_bf16 v[120:123], v[64:67], v[168:171], v[120:123]
	v_mfma_f32_16x16x32_bf16 v[108:111], v[48:51], v[176:179], v[108:111]
	v_mfma_f32_16x16x32_bf16 v[104:107], v[64:67], v[176:179], v[104:107]
	v_mfma_f32_16x16x32_bf16 v[92:95], v[48:51], v[184:187], v[92:95]
	v_mfma_f32_16x16x32_bf16 v[88:91], v[64:67], v[184:187], v[88:91]
	v_mfma_f32_16x16x32_bf16 v[132:135], v[52:55], v[164:167], v[132:135]
	v_mfma_f32_16x16x32_bf16 v[128:131], v[68:71], v[164:167], v[128:131]
	v_mfma_f32_16x16x32_bf16 v[124:127], v[52:55], v[172:175], v[124:127]
	v_mfma_f32_16x16x32_bf16 v[120:123], v[68:71], v[172:175], v[120:123]
	v_mfma_f32_16x16x32_bf16 v[108:111], v[52:55], v[180:183], v[108:111]
	v_mfma_f32_16x16x32_bf16 v[104:107], v[68:71], v[180:183], v[104:107]
	v_mfma_f32_16x16x32_bf16 v[92:95], v[52:55], v[188:191], v[92:95]
	v_mfma_f32_16x16x32_bf16 v[88:91], v[68:71], v[188:191], v[88:91]
	s_setprio 0
	s_setprio 1
	v_mfma_f32_16x16x32_bf16 v[140:143], v[144:147], v[160:163], v[140:143]
	v_mfma_f32_16x16x32_bf16 v[136:139], v[152:155], v[160:163], v[136:139]
	v_mfma_f32_16x16x32_bf16 v[116:119], v[144:147], v[168:171], v[116:119]
	v_mfma_f32_16x16x32_bf16 v[112:115], v[152:155], v[168:171], v[112:115]
	v_mfma_f32_16x16x32_bf16 v[100:103], v[144:147], v[176:179], v[100:103]
	v_mfma_f32_16x16x32_bf16 v[96:99], v[152:155], v[176:179], v[96:99]
	v_mfma_f32_16x16x32_bf16 v[84:87], v[144:147], v[184:187], v[84:87]
	v_mfma_f32_16x16x32_bf16 v[80:83], v[152:155], v[184:187], v[80:83]
	v_mfma_f32_16x16x32_bf16 v[140:143], v[148:151], v[164:167], v[140:143]
	v_mfma_f32_16x16x32_bf16 v[136:139], v[156:159], v[164:167], v[136:139]
	v_mfma_f32_16x16x32_bf16 v[116:119], v[148:151], v[172:175], v[116:119]
	v_mfma_f32_16x16x32_bf16 v[112:115], v[156:159], v[172:175], v[112:115]
	v_mfma_f32_16x16x32_bf16 v[100:103], v[148:151], v[180:183], v[100:103]
	v_mfma_f32_16x16x32_bf16 v[96:99], v[156:159], v[180:183], v[96:99]
	v_mfma_f32_16x16x32_bf16 v[84:87], v[148:151], v[188:191], v[84:87]
	v_mfma_f32_16x16x32_bf16 v[80:83], v[156:159], v[188:191], v[80:83]
	s_setprio 0
	s_barrier
; #define PG8_STAGE(bufoff, gbase, voff) do { _Pragma("unroll") for (int _i = 0; _i < 2; ++_i) \
;         __builtin_amdgcn_global_load_lds((const unsigned*)((const char*)(gbase) + (voff)[_i]), (PG8_LAS unsigned*)(lds + (bufoff) + ldsw + _i * (8 * USTR)), 16, 0, 0); } while (0)
; #define PG8_LDA(dst, b, h) do { _Pragma("unroll") for (int m = 0; m < 4; ++m) _Pragma("unroll") for (int k = 0; k < 2; ++k) dst[m][k] = *(const PG8_LAS bf16x8*)(lds + PG8_SA(b, h) + aoff + m * (2 * USTR) + k * 64); } while (0)
; #define PG8_MMA(ai, bj, At, Bt) do { __builtin_amdgcn_s_setprio(1); _Pragma("unroll") for (int m = 0; m < 4; ++m) _Pragma("unroll") for (int n = 0; n < 2; ++n) _Pragma("unroll") for (int k = 0; k < 2; ++k) \
;         acc[ai][bj][m][n] = __builtin_amdgcn_mfma_f32_16x16x32_bf16(Bt[n][k], At[m][k], acc[ai][bj][m][n], 0, 0, 0); __builtin_amdgcn_s_setprio(0); } while (0)
; #define PG8_WAIT_V(n) asm volatile("s_waitcnt vmcnt(" #n ")" ::: "memory")
; #define PG8_WAIT_L(n) asm volatile("s_waitcnt lgkmcnt(" #n ")" ::: "memory")
; #define PG8_BAR __builtin_amdgcn_s_barrier()
; #define PG8_SCHED __builtin_amdgcn_sched_barrier(0)
; template <class Epi, class Sched, bool ALIGN_EPI, bool SP2>
; __device__ __forceinline__ void gemm_phase(PG8_LAS unsigned char* lds, const Gemm g, const Sched& S, const Epi& E, int wid) {
;     ...
;             PG8_LDA(At, 1, 1); PG8_STAGE(PG8_SB(1, 0), b3, voffB); PG8_STAGE(PG8_SB(1, 1), b3 + hstepB, voffB); PG8_STAGE(PG8_SA(1, 0), a3, voffA);
;             PG8_WAIT_V(8); PG8_WAIT_L(0); PG8_BAR; PG8_MMA(1, 0, At, B0); PG8_MMA(1, 1, At, B1); PG8_BAR; PG8_SCHED;
	s_add_i32 s42, s69, s33
	v_lshl_add_u64 v[198:199], v[198:199], 0, s[6:7]
	s_mov_b32 m0, s42
	ds_read_b128 v[160:163], v241 offset:52224
	ds_read_b128 v[164:167], v241 offset:52288
	ds_read_b128 v[168:171], v241 offset:54400
	ds_read_b128 v[172:175], v241 offset:54464
	ds_read_b128 v[176:179], v241 offset:56576
	ds_read_b128 v[180:183], v241 offset:56640
	ds_read_b128 v[184:187], v241 offset:58752
	ds_read_b128 v[188:191], v241 offset:58816
	global_load_lds_dwordx4 v[198:199], off
	s_add_i32 m0, s42, 0x2200
	s_add_u32 s40, s40, 0xb0080
	v_lshl_add_u64 v[198:199], v[200:201], 0, s[6:7]
	s_addc_u32 s41, s41, 0
	s_add_i32 s42, s74, s33
	global_load_lds_dwordx4 v[198:199], off
	v_lshl_add_u64 v[198:199], s[40:41], 0, v[208:209]
	s_mov_b32 m0, s42
	s_nop 0
	global_load_lds_dwordx4 v[198:199], off
	v_lshl_add_u64 v[198:199], s[40:41], 0, v[210:211]
	s_add_i32 m0, s42, 0x2200
	s_nop 0
	global_load_lds_dwordx4 v[198:199], off
	v_lshl_add_u64 v[198:199], v[216:217], 0, s[6:7]
	s_mov_b32 m0, s57
	s_nop 0
	global_load_lds_dwordx4 v[198:199], off
	v_lshl_add_u64 v[198:199], v[218:219], 0, s[6:7]
	s_mov_b32 m0, s70
	s_nop 0
	global_load_lds_dwordx4 v[198:199], off
	s_waitcnt vmcnt(8)
	s_waitcnt lgkmcnt(0)
	s_barrier
	s_setprio 1
	s_waitcnt lgkmcnt(0)
	v_mfma_f32_16x16x32_bf16 v[76:79], v[48:51], v[160:163], v[76:79]
	v_mfma_f32_16x16x32_bf16 v[72:75], v[64:67], v[160:163], v[72:75]
	v_mfma_f32_16x16x32_bf16 v[60:63], v[48:51], v[168:171], v[60:63]
	v_mfma_f32_16x16x32_bf16 v[56:59], v[64:67], v[168:171], v[56:59]
	v_mfma_f32_16x16x32_bf16 v[24:27], v[48:51], v[176:179], v[24:27]
	v_mfma_f32_16x16x32_bf16 v[28:31], v[64:67], v[176:179], v[28:31]
	v_mfma_f32_16x16x32_bf16 v[8:11], v[48:51], v[184:187], v[8:11]
	v_mfma_f32_16x16x32_bf16 v[12:15], v[64:67], v[184:187], v[12:15]
	v_mfma_f32_16x16x32_bf16 v[76:79], v[52:55], v[164:167], v[76:79]
	v_mfma_f32_16x16x32_bf16 v[72:75], v[68:71], v[164:167], v[72:75]
	v_mfma_f32_16x16x32_bf16 v[60:63], v[52:55], v[172:175], v[60:63]
	v_mfma_f32_16x16x32_bf16 v[56:59], v[68:71], v[172:175], v[56:59]
	v_mfma_f32_16x16x32_bf16 v[24:27], v[52:55], v[180:183], v[24:27]
	v_mfma_f32_16x16x32_bf16 v[28:31], v[68:71], v[180:183], v[28:31]
	v_mfma_f32_16x16x32_bf16 v[8:11], v[52:55], v[188:191], v[8:11]
	v_mfma_f32_16x16x32_bf16 v[12:15], v[68:71], v[188:191], v[12:15]
	s_setprio 0
	s_setprio 1
	v_mfma_f32_16x16x32_bf16 v[40:43], v[144:147], v[160:163], v[40:43]
	v_mfma_f32_16x16x32_bf16 v[68:71], v[148:151], v[164:167], v[40:43]
	v_mfma_f32_16x16x32_bf16 v[40:43], v[152:155], v[160:163], v[44:47]
	v_mfma_f32_16x16x32_bf16 v[36:39], v[144:147], v[168:171], v[36:39]
	v_mfma_f32_16x16x32_bf16 v[32:35], v[152:155], v[168:171], v[32:35]
	v_mfma_f32_16x16x32_bf16 v[20:23], v[144:147], v[176:179], v[20:23]
	v_mfma_f32_16x16x32_bf16 v[16:19], v[152:155], v[176:179], v[16:19]
	v_mfma_f32_16x16x32_bf16 v[4:7], v[144:147], v[184:187], v[4:7]
	v_mfma_f32_16x16x32_bf16 v[0:3], v[152:155], v[184:187], v[0:3]
	v_mfma_f32_16x16x32_bf16 v[64:67], v[156:159], v[164:167], v[40:43]
	v_mfma_f32_16x16x32_bf16 v[36:39], v[148:151], v[172:175], v[36:39]
	v_mfma_f32_16x16x32_bf16 v[32:35], v[156:159], v[172:175], v[32:35]
	v_mfma_f32_16x16x32_bf16 v[20:23], v[148:151], v[180:183], v[20:23]
	v_mfma_f32_16x16x32_bf16 v[16:19], v[156:159], v[180:183], v[16:19]
	v_mfma_f32_16x16x32_bf16 v[4:7], v[148:151], v[188:191], v[4:7]
	v_mfma_f32_16x16x32_bf16 v[0:3], v[156:159], v[188:191], v[0:3]
	s_setprio 0
	s_barrier
	s_add_i32 s68, s68, 2
	s_add_u32 s38, s38, 0x100
	s_addc_u32 s39, s39, 0
	s_add_u32 s26, s26, 0x100
	s_addc_u32 s27, s27, 0
	s_cmp_gt_u32 s68, 41

; #define PG8_STAGE(bufoff, gbase, voff) do { _Pragma("unroll") for (int _i = 0; _i < 2; ++_i) \
;         __builtin_amdgcn_global_load_lds((const unsigned*)((const char*)(gbase) + (voff)[_i]), (PG8_LAS unsigned*)(lds + (bufoff) + ldsw + _i * (8 * USTR)), 16, 0, 0); } while (0)
; #define PG8_LDA(dst, b, h) do { _Pragma("unroll") for (int m = 0; m < 4; ++m) _Pragma("unroll") for (int k = 0; k < 2; ++k) dst[m][k] = *(const PG8_LAS bf16x8*)(lds + PG8_SA(b, h) + aoff + m * (2 * USTR) + k * 64); } while (0)
; #define PG8_LDB(dst, b, h) do { _Pragma("unroll") for (int n = 0; n < 2; ++n) _Pragma("unroll") for (int k = 0; k < 2; ++k) dst[n][k] = *(const PG8_LAS bf16x8*)(lds + PG8_SB(b, h) + boff + n * (2 * USTR) + k * 64); } while (0)
; #define PG8_SCHED __builtin_amdgcn_sched_barrier(0)
;     __host__ __device__ bool next(int i, Unit& u) const {
;         const long L = (long)i * G + c; if (L >= nwg) return false;
;         int wgid = (int)L; { const int q = nwg / NXCD, r = nwg % NXCD, xcd = wgid % NXCD, off = wgid / NXCD; wgid = (xcd < r ? xcd * (q + 1) : r * (q + 1) + (xcd - r) * q) + off; }
;         const int nig = WGM * nN, gid = wgid / nig, fm = gid * WGM, gsz = (nM - fm) < WGM ? (nM - fm) : WGM;
;         u.pm = fm + ((wgid % nig) % gsz); u.pn = (wgid % nig) / gsz; return true;
; template <class Epi, class Sched, bool ALIGN_EPI, bool SP2>
; __device__ __forceinline__ void gemm_phase(PG8_LAS unsigned char* lds, const Gemm g, const Sched& S, const Epi& E, int wid) {
;     ...
;             PG8_LDB(B0, 0, 0); PG8_LDB(B1, 0, 1); PG8_SCHED; PG8_LDA(At, 0, 0); PG8_STAGE(PG8_SA(1, 1), a1 + hstepA, voffA);
.LBB0_370:
	s_add_i32 s77, 0, 0x11000
	v_add_u32_e32 v94, s77, v161
	s_add_i32 s89, 0, 0x15400
	ds_read_b128 v[86:89], v94
	ds_read_b128 v[90:93], v94 offset:64
	ds_read_b128 v[164:167], v94 offset:2176
	ds_read_b128 v[168:171], v94 offset:2240
	v_add_u32_e32 v94, s89, v161
	ds_read_b128 v[172:175], v94
	ds_read_b128 v[176:179], v94 offset:64
	ds_read_b128 v[180:183], v94 offset:2176
	ds_read_b128 v[184:187], v94 offset:2240
	ds_read_b128 v[188:191], v163
	ds_read_b128 v[208:211], v163 offset:64
	ds_read_b128 v[212:215], v163 offset:2176
	ds_read_b128 v[216:219], v163 offset:2240
	ds_read_b128 v[220:223], v163 offset:4352
	ds_read_b128 v[224:227], v163 offset:4416
	ds_read_b128 v[228:231], v163 offset:6528
	ds_read_b128 v[242:245], v163 offset:6592
	s_add_i32 s72, s72, 1
	s_mul_i32 s23, s72, s13
	s_mul_hi_u32 s26, s72, s3
	s_add_i32 s23, s26, s23
	s_mul_i32 s26, s72, s3
	v_readlane_b32 s27, v251, 0
	s_add_u32 s26, s26, s27
	s_addc_u32 s27, s23, s58
	v_mov_b64_e32 v[0:1], 0xb00
	v_cmp_gt_i64_e32 vcc, s[26:27], v[202:203]
	v_cmp_lt_i64_e64 s[36:37], s[26:27], v[0:1]
	s_cbranch_vccnz .LBB0_372
	s_ashr_i32 s22, s26, 31
	s_lshr_b32 s22, s22, 29
	s_add_i32 s22, s26, s22
	s_ashr_i32 s23, s22, 3
	s_and_b32 s22, s22, -8
	s_sub_i32 s22, s26, s22
	s_cmp_lt_i32 s22, 0
	s_movk_i32 s26, 0x161
	s_cselect_b32 s26, s26, 0x160
	s_mul_i32 s22, s22, s26
	s_add_i32 s22, s22, s23
	s_mul_hi_i32 s23, s22, 0x2e8ba2e9
	s_lshr_b32 s26, s23, 31
	s_ashr_i32 s23, s23, 5
	s_add_i32 s23, s23, s26
	s_lshl_b32 s26, s23, 3
	s_sub_i32 s27, 0x80, s26
	s_min_i32 s27, s27, 8
	s_abs_i32 s40, s27
	v_cvt_f32_u32_e32 v0, s40
	s_sub_i32 s42, 0, s40
	s_mulk_i32 s23, 0xb0
	s_sub_i32 s23, s22, s23
	v_rcp_iflag_f32_e32 v0, v0
	s_abs_i32 s22, s23
	s_xor_b32 s41, s23, s27
	s_ashr_i32 s41, s41, 31
	v_mul_f32_e32 v0, 0x4f7ffffe, v0
	v_cvt_u32_f32_e32 v0, v0
	s_nop 0
	v_readfirstlane_b32 s43, v0
	s_mul_i32 s42, s42, s43
	s_mul_hi_u32 s42, s43, s42
	s_add_i32 s43, s43, s42
	s_mul_hi_u32 s42, s22, s43
	s_mul_i32 s43, s42, s40
	s_sub_i32 s22, s22, s43
	s_add_i32 s44, s42, 1
	s_sub_i32 s43, s22, s40
	s_cmp_ge_u32 s22, s40
	s_cselect_b32 s42, s44, s42
	s_cselect_b32 s22, s43, s22
	s_add_i32 s43, s42, 1
	s_cmp_ge_u32 s22, s40
	s_cselect_b32 s22, s43, s42
	s_xor_b32 s22, s22, s41
	s_sub_i32 s22, s22, s41
	s_mul_i32 s27, s22, s27
	s_sub_i32 s23, s23, s27
	s_add_i32 s40, s26, s23

; #define PG8_LAS __attribute__((address_space(3)))
; #define PG8_STAGE(bufoff, gbase, voff) do { _Pragma("unroll") for (int _i = 0; _i < 2; ++_i) \
;         __builtin_amdgcn_global_load_lds((const unsigned*)((const char*)(gbase) + (voff)[_i]), (PG8_LAS unsigned*)(lds + (bufoff) + ldsw + _i * (8 * USTR)), 16, 0, 0); } while (0)
; #define PG8_LDA(dst, b, h) do { _Pragma("unroll") for (int m = 0; m < 4; ++m) _Pragma("unroll") for (int k = 0; k < 2; ++k) dst[m][k] = *(const PG8_LAS bf16x8*)(lds + PG8_SA(b, h) + aoff + m * (2 * USTR) + k * 64); } while (0)
; #define PG8_LDB(dst, b, h) do { _Pragma("unroll") for (int n = 0; n < 2; ++n) _Pragma("unroll") for (int k = 0; k < 2; ++k) dst[n][k] = *(const PG8_LAS bf16x8*)(lds + PG8_SB(b, h) + boff + n * (2 * USTR) + k * 64); } while (0)
; template <class Epi, class Sched, bool ALIGN_EPI, bool SP2>
; __device__ __forceinline__ void gemm_phase(PG8_LAS unsigned char* lds, const Gemm g, const Sched& S, const Epi& E, int wid) {
;     ...
;             const bool last = (t == nt - 2);
;             const char* a1 = cA + (size_t)(t + 1) * kstep;
;             const char* a2 = last ? nA : cA + (size_t)(t + 2) * kstep; const char* b2 = last ? nB : cB + (size_t)(t + 2) * kstep;
;             const char* a3 = a2 + kstep; const char* b3 = b2 + kstep;
;             if constexpr (Epi::PRE == 1) { if (last) {
;                 const char* rsrc; const char* ssrc; E.pre(cur, rsrc, ssrc);
; #pragma unroll
;                 for (int _i = 0; _i < 2; ++_i) __builtin_amdgcn_global_load_lds((const unsigned*)(rsrc + (wid + 8 * _i) * 1024 + lane * 16), (PG8_LAS unsigned*)(lds + LDS_XOFF + (wid + 8 * _i) * 1024), 16, 0, 0);
;                 if (wid == 0) __builtin_amdgcn_global_load_lds((const unsigned*)(ssrc + lane * 16), (PG8_LAS unsigned*)(lds + LDS_XOFF + 16384), 16, 0, 0);
;             } }
;             if constexpr (SP2) {
;             PG8_LDB(B0, 0, 0); PG8_LDB(B1, 0, 1); PG8_SCHED; PG8_LDA(At, 0, 0); PG8_STAGE(PG8_SA(1, 1), a1 + hstepA, voffA);
;             PG8_WAIT_V(8); PG8_WAIT_L(0); PG8_BAR; PG8_MMA(0, 0, At, B0); PG8_MMA(0, 1, At, B1); PG8_BAR; PG8_SCHED;
;             PG8_LDA(At, 0, 1); PG8_STAGE(PG8_SB(0, 0), b2, voffB); PG8_STAGE(PG8_SB(0, 1), b2 + hstepB, voffB); PG8_STAGE(PG8_SA(0, 0), a2, voffA);
;             PG8_WAIT_V(8); PG8_WAIT_L(0); PG8_BAR; PG8_MMA(1, 0, At, B0); PG8_MMA(1, 1, At, B1); PG8_BAR; PG8_SCHED;
.Lhb_up:
	s_cmp_eq_u32 s76, 12
	s_cselect_b64 s[68:69], -1, 0
	s_add_u32 s70, s38, 0xfffc0080
	s_addc_u32 s71, s39, -1
	s_and_b64 s[68:69], s[68:69], exec
	s_cselect_b32 s71, s26, s71
	s_cselect_b32 s70, s27, s70
	s_cselect_b32 s69, s41, s75
	s_cselect_b32 s68, s73, s74
	s_add_i32 s77, 0, 0x11000
	s_add_i32 s89, 0, 0x15400
	v_lshl_add_u64 v[94:95], s[38:39], 0, v[154:155]
	s_add_i32 m0, s0, 0xcc00
	global_load_lds_dwordx4 v[94:95], off
	v_lshl_add_u64 v[94:95], s[38:39], 0, v[156:157]
	s_add_i32 m0, s0, 0xee00
	s_nop 0
	global_load_lds_dwordx4 v[94:95], off
	s_waitcnt vmcnt(8)
	s_waitcnt lgkmcnt(0)
	s_barrier
	s_setprio 1
	s_waitcnt lgkmcnt(0)
	v_mfma_f32_16x16x32_bf16 v[140:143], v[86:89], v[188:191], 0
	v_mfma_f32_16x16x32_bf16 v[136:139], v[164:167], v[188:191], 0
	v_mfma_f32_16x16x32_bf16 v[124:127], v[86:89], v[212:215], 0
	v_mfma_f32_16x16x32_bf16 v[120:123], v[164:167], v[212:215], 0
	v_mfma_f32_16x16x32_bf16 v[108:111], v[86:89], v[220:223], 0
	v_mfma_f32_16x16x32_bf16 v[104:107], v[164:167], v[220:223], 0
	v_mfma_f32_16x16x32_bf16 v[76:79], v[86:89], v[228:231], 0
	v_mfma_f32_16x16x32_bf16 v[72:75], v[164:167], v[228:231], 0
	v_mfma_f32_16x16x32_bf16 v[140:143], v[90:93], v[208:211], v[140:143]
	v_mfma_f32_16x16x32_bf16 v[136:139], v[168:171], v[208:211], v[136:139]
	v_mfma_f32_16x16x32_bf16 v[124:127], v[90:93], v[216:219], v[124:127]
	v_mfma_f32_16x16x32_bf16 v[120:123], v[168:171], v[216:219], v[120:123]
	v_mfma_f32_16x16x32_bf16 v[108:111], v[90:93], v[224:227], v[108:111]
	v_mfma_f32_16x16x32_bf16 v[104:107], v[168:171], v[224:227], v[104:107]
	v_mfma_f32_16x16x32_bf16 v[76:79], v[90:93], v[242:245], v[76:79]
	v_mfma_f32_16x16x32_bf16 v[72:75], v[168:171], v[242:245], v[72:75]
	s_setprio 0
	s_setprio 1
	v_mfma_f32_16x16x32_bf16 v[132:135], v[172:175], v[188:191], 0
	v_mfma_f32_16x16x32_bf16 v[128:131], v[180:183], v[188:191], 0
	v_mfma_f32_16x16x32_bf16 v[116:119], v[172:175], v[212:215], 0
	v_mfma_f32_16x16x32_bf16 v[112:115], v[180:183], v[212:215], 0
	v_mfma_f32_16x16x32_bf16 v[100:103], v[172:175], v[220:223], 0
	v_mfma_f32_16x16x32_bf16 v[94:97], v[180:183], v[220:223], 0
	v_mfma_f32_16x16x32_bf16 v[68:71], v[172:175], v[228:231], 0
	v_mfma_f32_16x16x32_bf16 v[64:67], v[180:183], v[228:231], 0
	v_mfma_f32_16x16x32_bf16 v[132:135], v[176:179], v[208:211], v[132:135]
	v_mfma_f32_16x16x32_bf16 v[128:131], v[184:187], v[208:211], v[128:131]
	v_mfma_f32_16x16x32_bf16 v[116:119], v[176:179], v[216:219], v[116:119]
	v_mfma_f32_16x16x32_bf16 v[112:115], v[184:187], v[216:219], v[112:115]
	v_mfma_f32_16x16x32_bf16 v[100:103], v[176:179], v[224:227], v[100:103]
	v_mfma_f32_16x16x32_bf16 v[94:97], v[184:187], v[224:227], v[94:97]
	v_mfma_f32_16x16x32_bf16 v[68:71], v[176:179], v[242:245], v[68:71]
	v_mfma_f32_16x16x32_bf16 v[64:67], v[184:187], v[242:245], v[64:67]
	s_setprio 0
	s_barrier
	s_add_i32 s77, s77, s33
	v_lshl_add_u64 v[158:159], s[68:69], 0, v[192:193]
	s_mov_b32 m0, s77
	ds_read_b128 v[188:191], v163 offset:17408
	ds_read_b128 v[208:211], v163 offset:17472
	ds_read_b128 v[212:215], v163 offset:19584
	ds_read_b128 v[216:219], v163 offset:19648
	ds_read_b128 v[220:223], v163 offset:21760
	ds_read_b128 v[224:227], v163 offset:21824
	ds_read_b128 v[228:231], v163 offset:23936
	ds_read_b128 v[242:245], v163 offset:24000
	global_load_lds_dwordx4 v[158:159], off
	s_add_i32 m0, s77, 0x2200
	s_add_u32 s78, s68, 0x40000
	v_lshl_add_u64 v[198:199], s[68:69], 0, v[144:145]
	s_addc_u32 s79, s69, 0
	s_add_i32 s77, s89, s33
	global_load_lds_dwordx4 v[198:199], off
	v_lshl_add_u64 v[98:99], s[78:79], 0, v[192:193]
	s_mov_b32 m0, s77
	v_lshl_add_u64 v[200:201], s[70:71], 0, v[148:149]
	global_load_lds_dwordx4 v[98:99], off
	v_lshl_add_u64 v[98:99], s[78:79], 0, v[144:145]
	s_add_i32 m0, s77, 0x2200
	v_lshl_add_u64 v[232:233], s[70:71], 0, v[146:147]
	global_load_lds_dwordx4 v[98:99], off
	s_mov_b32 m0, s0
	s_nop 0
	global_load_lds_dwordx4 v[200:201], off
	s_mov_b32 m0, s5
	s_nop 0
	global_load_lds_dwordx4 v[232:233], off
	s_waitcnt vmcnt(8)
	s_waitcnt lgkmcnt(0)
	s_barrier
	s_setprio 1
	s_waitcnt lgkmcnt(0)
	v_mfma_f32_16x16x32_bf16 v[60:63], v[86:89], v[188:191], 0
	v_mfma_f32_16x16x32_bf16 v[56:59], v[164:167], v[188:191], 0
	v_mfma_f32_16x16x32_bf16 v[44:47], v[86:89], v[212:215], 0
	v_mfma_f32_16x16x32_bf16 v[40:43], v[164:167], v[212:215], 0
	v_mfma_f32_16x16x32_bf16 v[28:31], v[86:89], v[220:223], 0
	v_mfma_f32_16x16x32_bf16 v[24:27], v[164:167], v[220:223], 0
	v_mfma_f32_16x16x32_bf16 v[12:15], v[86:89], v[228:231], 0
	v_mfma_f32_16x16x32_bf16 v[8:11], v[164:167], v[228:231], 0
	v_mfma_f32_16x16x32_bf16 v[60:63], v[90:93], v[208:211], v[60:63]
	v_mfma_f32_16x16x32_bf16 v[56:59], v[168:171], v[208:211], v[56:59]
	v_mfma_f32_16x16x32_bf16 v[44:47], v[90:93], v[216:219], v[44:47]
	v_mfma_f32_16x16x32_bf16 v[40:43], v[168:171], v[216:219], v[40:43]
	v_mfma_f32_16x16x32_bf16 v[28:31], v[90:93], v[224:227], v[28:31]
	v_mfma_f32_16x16x32_bf16 v[24:27], v[168:171], v[224:227], v[24:27]
	v_mfma_f32_16x16x32_bf16 v[12:15], v[90:93], v[242:245], v[12:15]
	v_mfma_f32_16x16x32_bf16 v[8:11], v[168:171], v[242:245], v[8:11]
	s_setprio 0
	s_setprio 1
	v_mfma_f32_16x16x32_bf16 v[52:55], v[172:175], v[188:191], 0
	v_mfma_f32_16x16x32_bf16 v[48:51], v[180:183], v[188:191], 0
	v_mfma_f32_16x16x32_bf16 v[36:39], v[172:175], v[212:215], 0
	v_mfma_f32_16x16x32_bf16 v[32:35], v[180:183], v[212:215], 0
	v_mfma_f32_16x16x32_bf16 v[20:23], v[172:175], v[220:223], 0
	v_mfma_f32_16x16x32_bf16 v[16:19], v[180:183], v[220:223], 0
	v_mfma_f32_16x16x32_bf16 v[4:7], v[172:175], v[228:231], 0
	v_mfma_f32_16x16x32_bf16 v[0:3], v[180:183], v[228:231], 0
	v_mfma_f32_16x16x32_bf16 v[52:55], v[176:179], v[208:211], v[52:55]
	v_mfma_f32_16x16x32_bf16 v[48:51], v[184:187], v[208:211], v[48:51]
	v_mfma_f32_16x16x32_bf16 v[36:39], v[176:179], v[216:219], v[36:39]
	v_mfma_f32_16x16x32_bf16 v[32:35], v[184:187], v[216:219], v[32:35]
	v_mfma_f32_16x16x32_bf16 v[20:23], v[176:179], v[224:227], v[20:23]
	v_mfma_f32_16x16x32_bf16 v[16:19], v[184:187], v[224:227], v[16:19]
	v_mfma_f32_16x16x32_bf16 v[4:7], v[176:179], v[242:245], v[4:7]
	v_mfma_f32_16x16x32_bf16 v[0:3], v[184:187], v[242:245], v[0:3]
	s_setprio 0
	s_barrier
; #define PG8_STAGE(bufoff, gbase, voff) do { _Pragma("unroll") for (int _i = 0; _i < 2; ++_i) \
;         __builtin_amdgcn_global_load_lds((const unsigned*)((const char*)(gbase) + (voff)[_i]), (PG8_LAS unsigned*)(lds + (bufoff) + ldsw + _i * (8 * USTR)), 16, 0, 0); } while (0)
; #define PG8_LDA(dst, b, h) do { _Pragma("unroll") for (int m = 0; m < 4; ++m) _Pragma("unroll") for (int k = 0; k < 2; ++k) dst[m][k] = *(const PG8_LAS bf16x8*)(lds + PG8_SA(b, h) + aoff + m * (2 * USTR) + k * 64); } while (0)
; #define PG8_LDB(dst, b, h) do { _Pragma("unroll") for (int n = 0; n < 2; ++n) _Pragma("unroll") for (int k = 0; k < 2; ++k) dst[n][k] = *(const PG8_LAS bf16x8*)(lds + PG8_SB(b, h) + boff + n * (2 * USTR) + k * 64); } while (0)
; #define PG8_MMA(ai, bj, At, Bt) do { __builtin_amdgcn_s_setprio(1); _Pragma("unroll") for (int m = 0; m < 4; ++m) _Pragma("unroll") for (int n = 0; n < 2; ++n) _Pragma("unroll") for (int k = 0; k < 2; ++k) \
;         acc[ai][bj][m][n] = __builtin_amdgcn_mfma_f32_16x16x32_bf16(Bt[n][k], At[m][k], acc[ai][bj][m][n], 0, 0, 0); __builtin_amdgcn_s_setprio(0); } while (0)
; #define PG8_WAIT_V(n) asm volatile("s_waitcnt vmcnt(" #n ")" ::: "memory")
; #define PG8_WAIT_L(n) asm volatile("s_waitcnt lgkmcnt(" #n ")" ::: "memory")
; #define PG8_BAR __builtin_amdgcn_s_barrier()
; #define PG8_SCHED __builtin_amdgcn_sched_barrier(0)
; template <class Epi, class Sched, bool ALIGN_EPI, bool SP2>
; __device__ __forceinline__ void gemm_phase(PG8_LAS unsigned char* lds, const Gemm g, const Sched& S, const Epi& E, int wid) {
;     ...
;             PG8_LDB(B0, 1, 0); PG8_LDB(B1, 1, 1); PG8_SCHED; PG8_LDA(At, 1, 0); PG8_STAGE(PG8_SA(0, 1), a2 + hstepA, voffA);
;             PG8_WAIT_V(8); PG8_WAIT_L(0); PG8_BAR; PG8_MMA(0, 0, At, B0); PG8_MMA(0, 1, At, B1); PG8_BAR; PG8_SCHED;
	s_add_i32 s77, 0, 0x19800
	v_add_u32_e32 v98, s77, v161
	s_add_i32 s78, 0, 0x1dc00
	ds_read_b128 v[86:89], v98
	ds_read_b128 v[90:93], v98 offset:64
	ds_read_b128 v[164:167], v98 offset:2176
	ds_read_b128 v[168:171], v98 offset:2240
	v_add_u32_e32 v98, s78, v161
	ds_read_b128 v[172:175], v98
	ds_read_b128 v[176:179], v98 offset:64
	ds_read_b128 v[180:183], v98 offset:2176
	ds_read_b128 v[184:187], v98 offset:2240
	s_add_u32 s70, s70, 0x40000
	s_addc_u32 s71, s71, 0
	s_mov_b32 m0, s10
	v_lshl_add_u64 v[98:99], s[70:71], 0, v[148:149]
	ds_read_b128 v[188:191], v163 offset:34816
	ds_read_b128 v[208:211], v163 offset:34880
	ds_read_b128 v[212:215], v163 offset:36992
	ds_read_b128 v[216:219], v163 offset:37056
	ds_read_b128 v[220:223], v163 offset:39168
	ds_read_b128 v[224:227], v163 offset:39232
	ds_read_b128 v[228:231], v163 offset:41344
	ds_read_b128 v[242:245], v163 offset:41408
	global_load_lds_dwordx4 v[98:99], off
	v_lshl_add_u64 v[98:99], s[70:71], 0, v[146:147]
	s_mov_b32 m0, s29
	s_nop 0
	global_load_lds_dwordx4 v[98:99], off
	s_waitcnt vmcnt(8)
	s_waitcnt lgkmcnt(0)
	s_barrier
	s_setprio 1
	s_waitcnt lgkmcnt(0)
	v_mfma_f32_16x16x32_bf16 v[140:143], v[86:89], v[188:191], v[140:143]
	v_mfma_f32_16x16x32_bf16 v[136:139], v[164:167], v[188:191], v[136:139]
	v_mfma_f32_16x16x32_bf16 v[124:127], v[86:89], v[212:215], v[124:127]
	v_mfma_f32_16x16x32_bf16 v[120:123], v[164:167], v[212:215], v[120:123]
	v_mfma_f32_16x16x32_bf16 v[108:111], v[86:89], v[220:223], v[108:111]
	v_mfma_f32_16x16x32_bf16 v[104:107], v[164:167], v[220:223], v[104:107]
	v_mfma_f32_16x16x32_bf16 v[76:79], v[86:89], v[228:231], v[76:79]
	v_mfma_f32_16x16x32_bf16 v[72:75], v[164:167], v[228:231], v[72:75]
	v_mfma_f32_16x16x32_bf16 v[140:143], v[90:93], v[208:211], v[140:143]
	v_mfma_f32_16x16x32_bf16 v[136:139], v[168:171], v[208:211], v[136:139]
	v_mfma_f32_16x16x32_bf16 v[124:127], v[90:93], v[216:219], v[124:127]
	v_mfma_f32_16x16x32_bf16 v[120:123], v[168:171], v[216:219], v[120:123]
	v_mfma_f32_16x16x32_bf16 v[108:111], v[90:93], v[224:227], v[108:111]
	v_mfma_f32_16x16x32_bf16 v[104:107], v[168:171], v[224:227], v[104:107]
	v_mfma_f32_16x16x32_bf16 v[76:79], v[90:93], v[242:245], v[76:79]
	v_mfma_f32_16x16x32_bf16 v[72:75], v[168:171], v[242:245], v[72:75]
	s_setprio 0
	s_setprio 1
	v_mfma_f32_16x16x32_bf16 v[132:135], v[172:175], v[188:191], v[132:135]
	v_mfma_f32_16x16x32_bf16 v[128:131], v[180:183], v[188:191], v[128:131]
	v_mfma_f32_16x16x32_bf16 v[116:119], v[172:175], v[212:215], v[116:119]
	v_mfma_f32_16x16x32_bf16 v[112:115], v[180:183], v[212:215], v[112:115]
	v_mfma_f32_16x16x32_bf16 v[98:101], v[172:175], v[220:223], v[100:103]
	v_mfma_f32_16x16x32_bf16 v[94:97], v[180:183], v[220:223], v[94:97]
	v_mfma_f32_16x16x32_bf16 v[68:71], v[172:175], v[228:231], v[68:71]
	v_mfma_f32_16x16x32_bf16 v[64:67], v[180:183], v[228:231], v[64:67]
	v_mfma_f32_16x16x32_bf16 v[132:135], v[176:179], v[208:211], v[132:135]
	v_mfma_f32_16x16x32_bf16 v[128:131], v[184:187], v[208:211], v[128:131]
	v_mfma_f32_16x16x32_bf16 v[116:119], v[176:179], v[216:219], v[116:119]
	v_mfma_f32_16x16x32_bf16 v[112:115], v[184:187], v[216:219], v[112:115]
	v_mfma_f32_16x16x32_bf16 v[100:103], v[176:179], v[224:227], v[98:101]
	v_mfma_f32_16x16x32_bf16 v[96:99], v[184:187], v[224:227], v[94:97]
	v_mfma_f32_16x16x32_bf16 v[68:71], v[176:179], v[242:245], v[68:71]
	v_mfma_f32_16x16x32_bf16 v[64:67], v[184:187], v[242:245], v[64:67]
	s_setprio 0
	s_barrier
; #define PG8_STAGE(bufoff, gbase, voff) do { _Pragma("unroll") for (int _i = 0; _i < 2; ++_i) \
;         __builtin_amdgcn_global_load_lds((const unsigned*)((const char*)(gbase) + (voff)[_i]), (PG8_LAS unsigned*)(lds + (bufoff) + ldsw + _i * (8 * USTR)), 16, 0, 0); } while (0)
; #define PG8_LDA(dst, b, h) do { _Pragma("unroll") for (int m = 0; m < 4; ++m) _Pragma("unroll") for (int k = 0; k < 2; ++k) dst[m][k] = *(const PG8_LAS bf16x8*)(lds + PG8_SA(b, h) + aoff + m * (2 * USTR) + k * 64); } while (0)
; #define PG8_MMA(ai, bj, At, Bt) do { __builtin_amdgcn_s_setprio(1); _Pragma("unroll") for (int m = 0; m < 4; ++m) _Pragma("unroll") for (int n = 0; n < 2; ++n) _Pragma("unroll") for (int k = 0; k < 2; ++k) \
;         acc[ai][bj][m][n] = __builtin_amdgcn_mfma_f32_16x16x32_bf16(Bt[n][k], At[m][k], acc[ai][bj][m][n], 0, 0, 0); __builtin_amdgcn_s_setprio(0); } while (0)
; #define PG8_WAIT_V(n) asm volatile("s_waitcnt vmcnt(" #n ")" ::: "memory")
; #define PG8_WAIT_L(n) asm volatile("s_waitcnt lgkmcnt(" #n ")" ::: "memory")
; #define PG8_BAR __builtin_amdgcn_s_barrier()
; #define PG8_SCHED __builtin_amdgcn_sched_barrier(0)
; template <class Epi, class Sched, bool ALIGN_EPI, bool SP2>
; __device__ __forceinline__ void gemm_phase(PG8_LAS unsigned char* lds, const Gemm g, const Sched& S, const Epi& E, int wid) {
;     ...
;         for (int t = 0; t < nt; t += 2) {
;     ...
;             PG8_LDA(At, 1, 1); PG8_STAGE(PG8_SB(1, 0), b3, voffB); PG8_STAGE(PG8_SB(1, 1), b3 + hstepB, voffB); PG8_STAGE(PG8_SA(1, 0), a3, voffA);
;             PG8_WAIT_V(8); PG8_WAIT_L(0); PG8_BAR; PG8_MMA(1, 0, At, B0); PG8_MMA(1, 1, At, B1); PG8_BAR; PG8_SCHED;
	s_add_i32 s70, s77, s33
	v_lshl_add_u64 v[94:95], v[158:159], 0, s[6:7]
	s_mov_b32 m0, s70
	ds_read_b128 v[188:191], v163 offset:52224
	ds_read_b128 v[208:211], v163 offset:52288
	ds_read_b128 v[212:215], v163 offset:54400
	ds_read_b128 v[216:219], v163 offset:54464
	ds_read_b128 v[220:223], v163 offset:56576
	ds_read_b128 v[224:227], v163 offset:56640
	ds_read_b128 v[228:231], v163 offset:58752
	ds_read_b128 v[242:245], v163 offset:58816
	global_load_lds_dwordx4 v[94:95], off
	s_add_i32 m0, s70, 0x2200
	s_add_u32 s68, s68, 0x40080
	v_lshl_add_u64 v[94:95], v[198:199], 0, s[6:7]
	s_addc_u32 s69, s69, 0
	s_add_i32 s70, s78, s33
	global_load_lds_dwordx4 v[94:95], off
	v_lshl_add_u64 v[94:95], s[68:69], 0, v[192:193]
	s_mov_b32 m0, s70
	s_nop 0
	global_load_lds_dwordx4 v[94:95], off
	v_lshl_add_u64 v[94:95], s[68:69], 0, v[144:145]
	s_add_i32 m0, s70, 0x2200
	s_nop 0
	global_load_lds_dwordx4 v[94:95], off
	v_lshl_add_u64 v[94:95], v[200:201], 0, s[6:7]
	s_mov_b32 m0, s56
	s_nop 0
	global_load_lds_dwordx4 v[94:95], off
	v_lshl_add_u64 v[94:95], v[232:233], 0, s[6:7]
	s_mov_b32 m0, s57
	s_nop 0
	global_load_lds_dwordx4 v[94:95], off
	s_waitcnt vmcnt(8)
	s_waitcnt lgkmcnt(0)
	s_barrier
	s_setprio 1
	s_waitcnt lgkmcnt(0)
	v_mfma_f32_16x16x32_bf16 v[60:63], v[86:89], v[188:191], v[60:63]
	v_mfma_f32_16x16x32_bf16 v[56:59], v[164:167], v[188:191], v[56:59]
	v_mfma_f32_16x16x32_bf16 v[44:47], v[86:89], v[212:215], v[44:47]
	v_mfma_f32_16x16x32_bf16 v[40:43], v[164:167], v[212:215], v[40:43]
	v_mfma_f32_16x16x32_bf16 v[28:31], v[86:89], v[220:223], v[28:31]
	v_mfma_f32_16x16x32_bf16 v[24:27], v[164:167], v[220:223], v[24:27]
	v_mfma_f32_16x16x32_bf16 v[12:15], v[86:89], v[228:231], v[12:15]
	v_mfma_f32_16x16x32_bf16 v[8:11], v[164:167], v[228:231], v[8:11]
	v_mfma_f32_16x16x32_bf16 v[60:63], v[90:93], v[208:211], v[60:63]
	v_mfma_f32_16x16x32_bf16 v[56:59], v[168:171], v[208:211], v[56:59]
	v_mfma_f32_16x16x32_bf16 v[44:47], v[90:93], v[216:219], v[44:47]
	v_mfma_f32_16x16x32_bf16 v[40:43], v[168:171], v[216:219], v[40:43]
	v_mfma_f32_16x16x32_bf16 v[28:31], v[90:93], v[224:227], v[28:31]
	v_mfma_f32_16x16x32_bf16 v[24:27], v[168:171], v[224:227], v[24:27]
	v_mfma_f32_16x16x32_bf16 v[12:15], v[90:93], v[242:245], v[12:15]
	v_mfma_f32_16x16x32_bf16 v[8:11], v[168:171], v[242:245], v[8:11]
	s_setprio 0
	s_setprio 1
	v_mfma_f32_16x16x32_bf16 v[52:55], v[172:175], v[188:191], v[52:55]
	v_mfma_f32_16x16x32_bf16 v[48:51], v[180:183], v[188:191], v[48:51]
	v_mfma_f32_16x16x32_bf16 v[36:39], v[172:175], v[212:215], v[36:39]
	v_mfma_f32_16x16x32_bf16 v[32:35], v[180:183], v[212:215], v[32:35]
	v_mfma_f32_16x16x32_bf16 v[20:23], v[172:175], v[220:223], v[20:23]
	v_mfma_f32_16x16x32_bf16 v[16:19], v[180:183], v[220:223], v[16:19]
	v_mfma_f32_16x16x32_bf16 v[4:7], v[172:175], v[228:231], v[4:7]
	v_mfma_f32_16x16x32_bf16 v[0:3], v[180:183], v[228:231], v[0:3]
	v_mfma_f32_16x16x32_bf16 v[52:55], v[176:179], v[208:211], v[52:55]
	v_mfma_f32_16x16x32_bf16 v[48:51], v[184:187], v[208:211], v[48:51]
	v_mfma_f32_16x16x32_bf16 v[36:39], v[176:179], v[216:219], v[36:39]
	v_mfma_f32_16x16x32_bf16 v[32:35], v[184:187], v[216:219], v[32:35]
	v_mfma_f32_16x16x32_bf16 v[20:23], v[176:179], v[224:227], v[20:23]
	v_mfma_f32_16x16x32_bf16 v[16:19], v[184:187], v[224:227], v[16:19]
	v_mfma_f32_16x16x32_bf16 v[4:7], v[176:179], v[242:245], v[4:7]
	v_mfma_f32_16x16x32_bf16 v[0:3], v[184:187], v[242:245], v[0:3]
	s_setprio 0
	s_barrier
	s_add_i32 s76, s76, 2
	s_add_u32 s38, s38, 0x100
	s_addc_u32 s39, s39, 0
	s_add_u32 s74, s74, 0x100
	s_addc_u32 s75, s75, 0
	s_cmp_gt_u32 s76, 13
	s_branch .LBB0_374
